# mixer output stores write-through (sc1) so the P2 seam has no dirty L2 lines to write back (on v38)
# speedup vs baseline: 1.0076x; 1.0027x over previous
; __device__ __forceinline__ unsigned pk2(float lo, float hi) { f32x2v v = {lo, hi}; b16x2v b = __builtin_convertvector(v, b16x2v); return __builtin_bit_cast(unsigned, b); }
; __device__ __forceinline__ f32x2v bf2(unsigned v) { return (f32x2v){bflo(v), bfhi(v)}; }
; template <int W>
; __device__ __forceinline__ void pool_prompt_w(const unsigned (&pin)[31], int t0, unsigned* dst  ) {
;     ...
;     for (int i = 0; i < W; ++i) s = s + bf2(pin[15 - i]);
; #pragma unroll
;     for (int t = 0; t < 16; ++t) {
;         if (t > 0) s = s + (bf2(pin[15 + t]) - bf2(pin[15 + t - W]));
;         const float cnt = (float)min(t0 + t + 1, W); const f32x2v cur = bf2(pin[15 + t]);
;         dst[(size_t)t * 512] = pk2(s.x / cnt - cur.x, s.y / cnt - cur.y);
.Lmx_pb0_0:
	v_cvt_pk_bf16_f32 v184, v182, v183
	global_store_dword v105, v184, s[76:77] offset:-3072 sc1
	v_lshlrev_b32_e32 v174, 16, v224
	v_and_b32_e32 v175, 0xffff0000, v224
	v_lshlrev_b32_e32 v176, 16, v222
	v_and_b32_e32 v177, 0xffff0000, v222
	v_pk_add_f32 v[178:179], v[174:175], v[176:177] neg_lo:[0,1] neg_hi:[0,1]
	v_pk_add_f32 v[172:173], v[172:173], v[178:179]
	v_pk_fma_f32 v[182:183], v[172:173], s[72:73], v[174:175] neg_lo:[0,0,1] neg_hi:[0,0,1]
	v_cvt_pk_bf16_f32 v185, v182, v183
	global_store_dword v105, v185, s[76:77] offset:-1024 sc1
	v_lshlrev_b32_e32 v174, 16, v225
	v_and_b32_e32 v175, 0xffff0000, v225
	v_lshlrev_b32_e32 v176, 16, v223
	v_and_b32_e32 v177, 0xffff0000, v223
	v_pk_add_f32 v[178:179], v[174:175], v[176:177] neg_lo:[0,1] neg_hi:[0,1]
	v_pk_add_f32 v[172:173], v[172:173], v[178:179]
	v_pk_fma_f32 v[182:183], v[172:173], s[72:73], v[174:175] neg_lo:[0,0,1] neg_hi:[0,0,1]
	v_cvt_pk_bf16_f32 v186, v182, v183
	global_store_dword v105, v186, s[76:77] offset:1024 sc1
	v_lshlrev_b32_e32 v174, 16, v226
	v_and_b32_e32 v175, 0xffff0000, v226
	v_lshlrev_b32_e32 v176, 16, v224
	v_and_b32_e32 v177, 0xffff0000, v224
	v_pk_add_f32 v[178:179], v[174:175], v[176:177] neg_lo:[0,1] neg_hi:[0,1]
	v_pk_add_f32 v[172:173], v[172:173], v[178:179]
	v_pk_fma_f32 v[182:183], v[172:173], s[72:73], v[174:175] neg_lo:[0,0,1] neg_hi:[0,0,1]
	v_cvt_pk_bf16_f32 v187, v182, v183
	global_store_dword v105, v187, s[76:77] offset:3072 sc1
	v_lshlrev_b32_e32 v174, 16, v227
	v_and_b32_e32 v175, 0xffff0000, v227
	v_lshlrev_b32_e32 v176, 16, v225
	v_and_b32_e32 v177, 0xffff0000, v225
	v_pk_add_f32 v[178:179], v[174:175], v[176:177] neg_lo:[0,1] neg_hi:[0,1]
	v_pk_add_f32 v[172:173], v[172:173], v[178:179]
	v_pk_fma_f32 v[182:183], v[172:173], s[72:73], v[174:175] neg_lo:[0,0,1] neg_hi:[0,0,1]
	v_cvt_pk_bf16_f32 v184, v182, v183
	s_add_u32 s76, s76, 0x2000
	s_addc_u32 s77, s77, 0
	global_store_dword v105, v184, s[76:77] offset:-3072 sc1
	v_lshlrev_b32_e32 v174, 16, v228
	v_and_b32_e32 v175, 0xffff0000, v228
	v_lshlrev_b32_e32 v176, 16, v226
	v_and_b32_e32 v177, 0xffff0000, v226
	v_pk_add_f32 v[178:179], v[174:175], v[176:177] neg_lo:[0,1] neg_hi:[0,1]
	v_pk_add_f32 v[172:173], v[172:173], v[178:179]
	v_pk_fma_f32 v[182:183], v[172:173], s[72:73], v[174:175] neg_lo:[0,0,1] neg_hi:[0,0,1]
	v_cvt_pk_bf16_f32 v185, v182, v183
	global_store_dword v105, v185, s[76:77] offset:-1024 sc1
	v_lshlrev_b32_e32 v174, 16, v229
	v_and_b32_e32 v175, 0xffff0000, v229
	v_lshlrev_b32_e32 v176, 16, v227
	v_and_b32_e32 v177, 0xffff0000, v227
	v_pk_add_f32 v[178:179], v[174:175], v[176:177] neg_lo:[0,1] neg_hi:[0,1]
	v_pk_add_f32 v[172:173], v[172:173], v[178:179]
	v_pk_fma_f32 v[182:183], v[172:173], s[72:73], v[174:175] neg_lo:[0,0,1] neg_hi:[0,0,1]
	v_cvt_pk_bf16_f32 v186, v182, v183
	global_store_dword v105, v186, s[76:77] offset:1024 sc1
	v_lshlrev_b32_e32 v174, 16, v230
	v_and_b32_e32 v175, 0xffff0000, v230
	v_lshlrev_b32_e32 v176, 16, v228
	v_and_b32_e32 v177, 0xffff0000, v228
	v_pk_add_f32 v[178:179], v[174:175], v[176:177] neg_lo:[0,1] neg_hi:[0,1]
	v_pk_add_f32 v[172:173], v[172:173], v[178:179]
	v_pk_fma_f32 v[182:183], v[172:173], s[72:73], v[174:175] neg_lo:[0,0,1] neg_hi:[0,0,1]
	v_cvt_pk_bf16_f32 v187, v182, v183
	global_store_dword v105, v187, s[76:77] offset:3072 sc1
	v_lshlrev_b32_e32 v174, 16, v231
	v_and_b32_e32 v175, 0xffff0000, v231
	v_lshlrev_b32_e32 v176, 16, v229
	v_and_b32_e32 v177, 0xffff0000, v229
	v_pk_add_f32 v[178:179], v[174:175], v[176:177] neg_lo:[0,1] neg_hi:[0,1]
	v_pk_add_f32 v[172:173], v[172:173], v[178:179]
	v_pk_fma_f32 v[182:183], v[172:173], s[72:73], v[174:175] neg_lo:[0,0,1] neg_hi:[0,0,1]
	v_cvt_pk_bf16_f32 v184, v182, v183
	s_add_u32 s76, s76, 0x2000
	s_addc_u32 s77, s77, 0
	s_waitcnt vmcnt(40)
; __device__ __forceinline__ unsigned pk2(float lo, float hi) { f32x2v v = {lo, hi}; b16x2v b = __builtin_convertvector(v, b16x2v); return __builtin_bit_cast(unsigned, b); }
; __device__ __forceinline__ f32x2v bf2(unsigned v) { return (f32x2v){bflo(v), bfhi(v)}; }
; template <int W>
; __device__ __forceinline__ void pool_prompt_w(const unsigned (&pin)[31], int t0, unsigned* dst  ) {
;     ...
;     for (int i = 0; i < W; ++i) s = s + bf2(pin[15 - i]);
; #pragma unroll
;     for (int t = 0; t < 16; ++t) {
;         if (t > 0) s = s + (bf2(pin[15 + t]) - bf2(pin[15 + t - W]));
;         const float cnt = (float)min(t0 + t + 1, W); const f32x2v cur = bf2(pin[15 + t]);
;         dst[(size_t)t * 512] = pk2(s.x / cnt - cur.x, s.y / cnt - cur.y);
	global_store_dword v105, v184, s[76:77] offset:-3072 sc1
	v_lshlrev_b32_e32 v174, 16, v232
	v_and_b32_e32 v175, 0xffff0000, v232
	v_lshlrev_b32_e32 v176, 16, v230
	v_and_b32_e32 v177, 0xffff0000, v230
	v_pk_add_f32 v[178:179], v[174:175], v[176:177] neg_lo:[0,1] neg_hi:[0,1]
	v_pk_add_f32 v[172:173], v[172:173], v[178:179]
	v_pk_fma_f32 v[182:183], v[172:173], s[72:73], v[174:175] neg_lo:[0,0,1] neg_hi:[0,0,1]
	v_cvt_pk_bf16_f32 v185, v182, v183
	global_store_dword v105, v185, s[76:77] offset:-1024 sc1
	v_lshlrev_b32_e32 v174, 16, v233
	v_and_b32_e32 v175, 0xffff0000, v233
	v_lshlrev_b32_e32 v176, 16, v231
	v_and_b32_e32 v177, 0xffff0000, v231
	v_pk_add_f32 v[178:179], v[174:175], v[176:177] neg_lo:[0,1] neg_hi:[0,1]
	v_pk_add_f32 v[172:173], v[172:173], v[178:179]
	v_pk_fma_f32 v[182:183], v[172:173], s[72:73], v[174:175] neg_lo:[0,0,1] neg_hi:[0,0,1]
	v_cvt_pk_bf16_f32 v186, v182, v183
	global_store_dword v105, v186, s[76:77] offset:1024 sc1
	v_lshlrev_b32_e32 v174, 16, v234
	v_and_b32_e32 v175, 0xffff0000, v234
	v_lshlrev_b32_e32 v176, 16, v232
	v_and_b32_e32 v177, 0xffff0000, v232
	v_pk_add_f32 v[178:179], v[174:175], v[176:177] neg_lo:[0,1] neg_hi:[0,1]
	v_pk_add_f32 v[172:173], v[172:173], v[178:179]
	v_pk_fma_f32 v[182:183], v[172:173], s[72:73], v[174:175] neg_lo:[0,0,1] neg_hi:[0,0,1]
	v_cvt_pk_bf16_f32 v187, v182, v183
	global_store_dword v105, v187, s[76:77] offset:3072 sc1
	v_lshlrev_b32_e32 v174, 16, v235
	v_and_b32_e32 v175, 0xffff0000, v235
	v_lshlrev_b32_e32 v176, 16, v233
	v_and_b32_e32 v177, 0xffff0000, v233
	v_pk_add_f32 v[178:179], v[174:175], v[176:177] neg_lo:[0,1] neg_hi:[0,1]
	v_pk_add_f32 v[172:173], v[172:173], v[178:179]
	v_pk_fma_f32 v[182:183], v[172:173], s[72:73], v[174:175] neg_lo:[0,0,1] neg_hi:[0,0,1]
	v_cvt_pk_bf16_f32 v184, v182, v183
	s_add_u32 s76, s76, 0x2000
	s_addc_u32 s77, s77, 0
	global_store_dword v105, v184, s[76:77] offset:-3072 sc1
	v_lshlrev_b32_e32 v174, 16, v236
	v_and_b32_e32 v175, 0xffff0000, v236
	v_lshlrev_b32_e32 v176, 16, v234
	v_and_b32_e32 v177, 0xffff0000, v234
	v_pk_add_f32 v[178:179], v[174:175], v[176:177] neg_lo:[0,1] neg_hi:[0,1]
	v_pk_add_f32 v[172:173], v[172:173], v[178:179]
	v_pk_fma_f32 v[182:183], v[172:173], s[72:73], v[174:175] neg_lo:[0,0,1] neg_hi:[0,0,1]
	v_cvt_pk_bf16_f32 v185, v182, v183
	global_store_dword v105, v185, s[76:77] offset:-1024 sc1
	v_lshlrev_b32_e32 v174, 16, v237
	v_and_b32_e32 v175, 0xffff0000, v237
	v_lshlrev_b32_e32 v176, 16, v235
	v_and_b32_e32 v177, 0xffff0000, v235
	v_pk_add_f32 v[178:179], v[174:175], v[176:177] neg_lo:[0,1] neg_hi:[0,1]
	v_pk_add_f32 v[172:173], v[172:173], v[178:179]
	v_pk_fma_f32 v[182:183], v[172:173], s[72:73], v[174:175] neg_lo:[0,0,1] neg_hi:[0,0,1]
	v_cvt_pk_bf16_f32 v186, v182, v183
	global_store_dword v105, v186, s[76:77] offset:1024 sc1
	v_lshlrev_b32_e32 v174, 16, v238
	v_and_b32_e32 v175, 0xffff0000, v238
	v_lshlrev_b32_e32 v176, 16, v236
	v_and_b32_e32 v177, 0xffff0000, v236
	v_pk_add_f32 v[178:179], v[174:175], v[176:177] neg_lo:[0,1] neg_hi:[0,1]
	v_pk_add_f32 v[172:173], v[172:173], v[178:179]
	v_pk_fma_f32 v[182:183], v[172:173], s[72:73], v[174:175] neg_lo:[0,0,1] neg_hi:[0,0,1]
	v_cvt_pk_bf16_f32 v187, v182, v183
	global_store_dword v105, v187, s[76:77] offset:3072 sc1
	s_branch .Lmx_pool_done

; __device__ __forceinline__ unsigned pk2(float lo, float hi) { f32x2v v = {lo, hi}; b16x2v b = __builtin_convertvector(v, b16x2v); return __builtin_bit_cast(unsigned, b); }
; __device__ __forceinline__ f32x2v bf2(unsigned v) { return (f32x2v){bflo(v), bfhi(v)}; }
; template <int W>
; __device__ __forceinline__ void pool_prompt_w(const unsigned (&pin)[31], int t0, unsigned* dst  ) {
;     ...
;     for (int i = 0; i < W; ++i) s = s + bf2(pin[15 - i]);
; #pragma unroll
;     for (int t = 0; t < 16; ++t) {
;         if (t > 0) s = s + (bf2(pin[15 + t]) - bf2(pin[15 + t - W]));
;         const float cnt = (float)min(t0 + t + 1, W); const f32x2v cur = bf2(pin[15 + t]);
;         dst[(size_t)t * 512] = pk2(s.x / cnt - cur.x, s.y / cnt - cur.y);
.Lmx_pb1_0:
	v_cvt_pk_bf16_f32 v184, v182, v183
	global_store_dword v105, v184, s[76:77] offset:-3072 sc1
	v_lshlrev_b32_e32 v174, 16, v224
	v_and_b32_e32 v175, 0xffff0000, v224
	v_lshlrev_b32_e32 v176, 16, v220
	v_and_b32_e32 v177, 0xffff0000, v220
	v_pk_add_f32 v[178:179], v[174:175], v[176:177] neg_lo:[0,1] neg_hi:[0,1]
	v_pk_add_f32 v[172:173], v[172:173], v[178:179]
	s_cmp_eq_u32 s64, 0
	s_cbranch_scc1 .Lmx_ps1_1
	v_pk_fma_f32 v[182:183], v[172:173], s[72:73], v[174:175] neg_lo:[0,0,1] neg_hi:[0,0,1]
.Lmx_pb1_1:
	v_cvt_pk_bf16_f32 v185, v182, v183
	global_store_dword v105, v185, s[76:77] offset:-1024 sc1
	v_lshlrev_b32_e32 v174, 16, v225
	v_and_b32_e32 v175, 0xffff0000, v225
	v_lshlrev_b32_e32 v176, 16, v221
	v_and_b32_e32 v177, 0xffff0000, v221
	v_pk_add_f32 v[178:179], v[174:175], v[176:177] neg_lo:[0,1] neg_hi:[0,1]
	v_pk_add_f32 v[172:173], v[172:173], v[178:179]
	s_cmp_eq_u32 s64, 0
	s_cbranch_scc1 .Lmx_ps1_2
	v_pk_fma_f32 v[182:183], v[172:173], s[72:73], v[174:175] neg_lo:[0,0,1] neg_hi:[0,0,1]
; __device__ __forceinline__ unsigned pk2(float lo, float hi) { f32x2v v = {lo, hi}; b16x2v b = __builtin_convertvector(v, b16x2v); return __builtin_bit_cast(unsigned, b); }
; __device__ __forceinline__ f32x2v bf2(unsigned v) { return (f32x2v){bflo(v), bfhi(v)}; }
; template <int W>
; __device__ __forceinline__ void pool_prompt_w(const unsigned (&pin)[31], int t0, unsigned* dst  ) {
;     ...
;     for (int i = 0; i < W; ++i) s = s + bf2(pin[15 - i]);
; #pragma unroll
;     for (int t = 0; t < 16; ++t) {
;         if (t > 0) s = s + (bf2(pin[15 + t]) - bf2(pin[15 + t - W]));
;         const float cnt = (float)min(t0 + t + 1, W); const f32x2v cur = bf2(pin[15 + t]);
;         dst[(size_t)t * 512] = pk2(s.x / cnt - cur.x, s.y / cnt - cur.y);
.Lmx_pb1_2:
	v_cvt_pk_bf16_f32 v186, v182, v183
	global_store_dword v105, v186, s[76:77] offset:1024 sc1
	v_lshlrev_b32_e32 v174, 16, v226
	v_and_b32_e32 v175, 0xffff0000, v226
	v_lshlrev_b32_e32 v176, 16, v222
	v_and_b32_e32 v177, 0xffff0000, v222
	v_pk_add_f32 v[178:179], v[174:175], v[176:177] neg_lo:[0,1] neg_hi:[0,1]
	v_pk_add_f32 v[172:173], v[172:173], v[178:179]
	v_pk_fma_f32 v[182:183], v[172:173], s[72:73], v[174:175] neg_lo:[0,0,1] neg_hi:[0,0,1]
	v_cvt_pk_bf16_f32 v187, v182, v183
	global_store_dword v105, v187, s[76:77] offset:3072 sc1
	v_lshlrev_b32_e32 v174, 16, v227
	v_and_b32_e32 v175, 0xffff0000, v227
	v_lshlrev_b32_e32 v176, 16, v223
	v_and_b32_e32 v177, 0xffff0000, v223
	v_pk_add_f32 v[178:179], v[174:175], v[176:177] neg_lo:[0,1] neg_hi:[0,1]
	v_pk_add_f32 v[172:173], v[172:173], v[178:179]
	v_pk_fma_f32 v[182:183], v[172:173], s[72:73], v[174:175] neg_lo:[0,0,1] neg_hi:[0,0,1]
	v_cvt_pk_bf16_f32 v184, v182, v183
	s_add_u32 s76, s76, 0x2000
	s_addc_u32 s77, s77, 0
	global_store_dword v105, v184, s[76:77] offset:-3072 sc1
	v_lshlrev_b32_e32 v174, 16, v228
	v_and_b32_e32 v175, 0xffff0000, v228
	v_lshlrev_b32_e32 v176, 16, v224
	v_and_b32_e32 v177, 0xffff0000, v224
	v_pk_add_f32 v[178:179], v[174:175], v[176:177] neg_lo:[0,1] neg_hi:[0,1]
	v_pk_add_f32 v[172:173], v[172:173], v[178:179]
	v_pk_fma_f32 v[182:183], v[172:173], s[72:73], v[174:175] neg_lo:[0,0,1] neg_hi:[0,0,1]
	v_cvt_pk_bf16_f32 v185, v182, v183
	global_store_dword v105, v185, s[76:77] offset:-1024 sc1
	v_lshlrev_b32_e32 v174, 16, v229
	v_and_b32_e32 v175, 0xffff0000, v229
	v_lshlrev_b32_e32 v176, 16, v225
	v_and_b32_e32 v177, 0xffff0000, v225
	v_pk_add_f32 v[178:179], v[174:175], v[176:177] neg_lo:[0,1] neg_hi:[0,1]
	v_pk_add_f32 v[172:173], v[172:173], v[178:179]
	v_pk_fma_f32 v[182:183], v[172:173], s[72:73], v[174:175] neg_lo:[0,0,1] neg_hi:[0,0,1]
	v_cvt_pk_bf16_f32 v186, v182, v183
	global_store_dword v105, v186, s[76:77] offset:1024 sc1
	v_lshlrev_b32_e32 v174, 16, v230
	v_and_b32_e32 v175, 0xffff0000, v230
	v_lshlrev_b32_e32 v176, 16, v226
	v_and_b32_e32 v177, 0xffff0000, v226
	v_pk_add_f32 v[178:179], v[174:175], v[176:177] neg_lo:[0,1] neg_hi:[0,1]
	v_pk_add_f32 v[172:173], v[172:173], v[178:179]
	v_pk_fma_f32 v[182:183], v[172:173], s[72:73], v[174:175] neg_lo:[0,0,1] neg_hi:[0,0,1]
	v_cvt_pk_bf16_f32 v187, v182, v183
	global_store_dword v105, v187, s[76:77] offset:3072 sc1
	v_lshlrev_b32_e32 v174, 16, v231
	v_and_b32_e32 v175, 0xffff0000, v231
	v_lshlrev_b32_e32 v176, 16, v227
	v_and_b32_e32 v177, 0xffff0000, v227
	v_pk_add_f32 v[178:179], v[174:175], v[176:177] neg_lo:[0,1] neg_hi:[0,1]
	v_pk_add_f32 v[172:173], v[172:173], v[178:179]
	v_pk_fma_f32 v[182:183], v[172:173], s[72:73], v[174:175] neg_lo:[0,0,1] neg_hi:[0,0,1]
	v_cvt_pk_bf16_f32 v184, v182, v183
	s_add_u32 s76, s76, 0x2000
	s_addc_u32 s77, s77, 0
	s_waitcnt vmcnt(40)
	global_store_dword v105, v184, s[76:77] offset:-3072 sc1
	v_lshlrev_b32_e32 v174, 16, v232
	v_and_b32_e32 v175, 0xffff0000, v232
	v_lshlrev_b32_e32 v176, 16, v228
	v_and_b32_e32 v177, 0xffff0000, v228
	v_pk_add_f32 v[178:179], v[174:175], v[176:177] neg_lo:[0,1] neg_hi:[0,1]
	v_pk_add_f32 v[172:173], v[172:173], v[178:179]
	v_pk_fma_f32 v[182:183], v[172:173], s[72:73], v[174:175] neg_lo:[0,0,1] neg_hi:[0,0,1]
	v_cvt_pk_bf16_f32 v185, v182, v183
	global_store_dword v105, v185, s[76:77] offset:-1024 sc1
	v_lshlrev_b32_e32 v174, 16, v233
	v_and_b32_e32 v175, 0xffff0000, v233
	v_lshlrev_b32_e32 v176, 16, v229
	v_and_b32_e32 v177, 0xffff0000, v229
	v_pk_add_f32 v[178:179], v[174:175], v[176:177] neg_lo:[0,1] neg_hi:[0,1]
	v_pk_add_f32 v[172:173], v[172:173], v[178:179]
	v_pk_fma_f32 v[182:183], v[172:173], s[72:73], v[174:175] neg_lo:[0,0,1] neg_hi:[0,0,1]
	v_cvt_pk_bf16_f32 v186, v182, v183
	global_store_dword v105, v186, s[76:77] offset:1024 sc1
	v_lshlrev_b32_e32 v174, 16, v234
	v_and_b32_e32 v175, 0xffff0000, v234
	v_lshlrev_b32_e32 v176, 16, v230
	v_and_b32_e32 v177, 0xffff0000, v230
	v_pk_add_f32 v[178:179], v[174:175], v[176:177] neg_lo:[0,1] neg_hi:[0,1]
	v_pk_add_f32 v[172:173], v[172:173], v[178:179]
	v_pk_fma_f32 v[182:183], v[172:173], s[72:73], v[174:175] neg_lo:[0,0,1] neg_hi:[0,0,1]
	v_cvt_pk_bf16_f32 v187, v182, v183
	global_store_dword v105, v187, s[76:77] offset:3072 sc1
	v_lshlrev_b32_e32 v174, 16, v235
	v_and_b32_e32 v175, 0xffff0000, v235
	v_lshlrev_b32_e32 v176, 16, v231
	v_and_b32_e32 v177, 0xffff0000, v231
	v_pk_add_f32 v[178:179], v[174:175], v[176:177] neg_lo:[0,1] neg_hi:[0,1]
	v_pk_add_f32 v[172:173], v[172:173], v[178:179]
	v_pk_fma_f32 v[182:183], v[172:173], s[72:73], v[174:175] neg_lo:[0,0,1] neg_hi:[0,0,1]
	v_cvt_pk_bf16_f32 v184, v182, v183
	s_add_u32 s76, s76, 0x2000
	s_addc_u32 s77, s77, 0
	global_store_dword v105, v184, s[76:77] offset:-3072 sc1
	v_lshlrev_b32_e32 v174, 16, v236
	v_and_b32_e32 v175, 0xffff0000, v236
	v_lshlrev_b32_e32 v176, 16, v232
	v_and_b32_e32 v177, 0xffff0000, v232
	v_pk_add_f32 v[178:179], v[174:175], v[176:177] neg_lo:[0,1] neg_hi:[0,1]
	v_pk_add_f32 v[172:173], v[172:173], v[178:179]
	v_pk_fma_f32 v[182:183], v[172:173], s[72:73], v[174:175] neg_lo:[0,0,1] neg_hi:[0,0,1]
	v_cvt_pk_bf16_f32 v185, v182, v183
	global_store_dword v105, v185, s[76:77] offset:-1024 sc1
	v_lshlrev_b32_e32 v174, 16, v237
	v_and_b32_e32 v175, 0xffff0000, v237
	v_lshlrev_b32_e32 v176, 16, v233
	v_and_b32_e32 v177, 0xffff0000, v233
	v_pk_add_f32 v[178:179], v[174:175], v[176:177] neg_lo:[0,1] neg_hi:[0,1]
	v_pk_add_f32 v[172:173], v[172:173], v[178:179]
	v_pk_fma_f32 v[182:183], v[172:173], s[72:73], v[174:175] neg_lo:[0,0,1] neg_hi:[0,0,1]
	v_cvt_pk_bf16_f32 v186, v182, v183
	global_store_dword v105, v186, s[76:77] offset:1024 sc1
	v_lshlrev_b32_e32 v174, 16, v238
	v_and_b32_e32 v175, 0xffff0000, v238
	v_lshlrev_b32_e32 v176, 16, v234
	v_and_b32_e32 v177, 0xffff0000, v234
	v_pk_add_f32 v[178:179], v[174:175], v[176:177] neg_lo:[0,1] neg_hi:[0,1]
	v_pk_add_f32 v[172:173], v[172:173], v[178:179]
	v_pk_fma_f32 v[182:183], v[172:173], s[72:73], v[174:175] neg_lo:[0,0,1] neg_hi:[0,0,1]
	v_cvt_pk_bf16_f32 v187, v182, v183
	global_store_dword v105, v187, s[76:77] offset:3072 sc1
	s_branch .Lmx_pool_done

; __device__ __forceinline__ unsigned pk2(float lo, float hi) { f32x2v v = {lo, hi}; b16x2v b = __builtin_convertvector(v, b16x2v); return __builtin_bit_cast(unsigned, b); }
; __device__ __forceinline__ f32x2v bf2(unsigned v) { return (f32x2v){bflo(v), bfhi(v)}; }
; template <int W>
; __device__ __forceinline__ void pool_prompt_w(const unsigned (&pin)[31], int t0, unsigned* dst  ) {
;     ...
;     for (int i = 0; i < W; ++i) s = s + bf2(pin[15 - i]);
; #pragma unroll
;     for (int t = 0; t < 16; ++t) {
;         if (t > 0) s = s + (bf2(pin[15 + t]) - bf2(pin[15 + t - W]));
;         const float cnt = (float)min(t0 + t + 1, W); const f32x2v cur = bf2(pin[15 + t]);
;         dst[(size_t)t * 512] = pk2(s.x / cnt - cur.x, s.y / cnt - cur.y);
.Lmx_pb2_0:
	v_cvt_pk_bf16_f32 v184, v182, v183
	global_store_dword v105, v184, s[76:77] offset:-3072 sc1
	v_lshlrev_b32_e32 v174, 16, v224
	v_and_b32_e32 v175, 0xffff0000, v224
	v_lshlrev_b32_e32 v176, 16, v216
	v_and_b32_e32 v177, 0xffff0000, v216
	v_pk_add_f32 v[178:179], v[174:175], v[176:177] neg_lo:[0,1] neg_hi:[0,1]
	v_pk_add_f32 v[172:173], v[172:173], v[178:179]
	s_cmp_eq_u32 s64, 0
	s_cbranch_scc1 .Lmx_ps2_1
	v_pk_fma_f32 v[182:183], v[172:173], s[72:73], v[174:175] neg_lo:[0,0,1] neg_hi:[0,0,1]
.Lmx_pb2_1:
	v_cvt_pk_bf16_f32 v185, v182, v183
	global_store_dword v105, v185, s[76:77] offset:-1024 sc1
	v_lshlrev_b32_e32 v174, 16, v225
	v_and_b32_e32 v175, 0xffff0000, v225
	v_lshlrev_b32_e32 v176, 16, v217
	v_and_b32_e32 v177, 0xffff0000, v217
	v_pk_add_f32 v[178:179], v[174:175], v[176:177] neg_lo:[0,1] neg_hi:[0,1]
	v_pk_add_f32 v[172:173], v[172:173], v[178:179]
	s_cmp_eq_u32 s64, 0
	s_cbranch_scc1 .Lmx_ps2_2
	v_pk_fma_f32 v[182:183], v[172:173], s[72:73], v[174:175] neg_lo:[0,0,1] neg_hi:[0,0,1]
.Lmx_pb2_2:
	v_cvt_pk_bf16_f32 v186, v182, v183
	global_store_dword v105, v186, s[76:77] offset:1024 sc1
	v_lshlrev_b32_e32 v174, 16, v226
	v_and_b32_e32 v175, 0xffff0000, v226
	v_lshlrev_b32_e32 v176, 16, v218
	v_and_b32_e32 v177, 0xffff0000, v218
	v_pk_add_f32 v[178:179], v[174:175], v[176:177] neg_lo:[0,1] neg_hi:[0,1]
	v_pk_add_f32 v[172:173], v[172:173], v[178:179]
	s_cmp_eq_u32 s64, 0
	s_cbranch_scc1 .Lmx_ps2_3
	v_pk_fma_f32 v[182:183], v[172:173], s[72:73], v[174:175] neg_lo:[0,0,1] neg_hi:[0,0,1]
.Lmx_pb2_3:
	v_cvt_pk_bf16_f32 v187, v182, v183
	global_store_dword v105, v187, s[76:77] offset:3072 sc1
	v_lshlrev_b32_e32 v174, 16, v227
	v_and_b32_e32 v175, 0xffff0000, v227
	v_lshlrev_b32_e32 v176, 16, v219
	v_and_b32_e32 v177, 0xffff0000, v219
	v_pk_add_f32 v[178:179], v[174:175], v[176:177] neg_lo:[0,1] neg_hi:[0,1]
	v_pk_add_f32 v[172:173], v[172:173], v[178:179]
	s_cmp_eq_u32 s64, 0
	s_cbranch_scc1 .Lmx_ps2_4
	v_pk_fma_f32 v[182:183], v[172:173], s[72:73], v[174:175] neg_lo:[0,0,1] neg_hi:[0,0,1]
.Lmx_pb2_4:
	v_cvt_pk_bf16_f32 v184, v182, v183
	s_add_u32 s76, s76, 0x2000
	s_addc_u32 s77, s77, 0
	global_store_dword v105, v184, s[76:77] offset:-3072 sc1
	v_lshlrev_b32_e32 v174, 16, v228
	v_and_b32_e32 v175, 0xffff0000, v228
	v_lshlrev_b32_e32 v176, 16, v220
	v_and_b32_e32 v177, 0xffff0000, v220
	v_pk_add_f32 v[178:179], v[174:175], v[176:177] neg_lo:[0,1] neg_hi:[0,1]
	v_pk_add_f32 v[172:173], v[172:173], v[178:179]
	s_cmp_eq_u32 s64, 0
	s_cbranch_scc1 .Lmx_ps2_5
	v_pk_fma_f32 v[182:183], v[172:173], s[72:73], v[174:175] neg_lo:[0,0,1] neg_hi:[0,0,1]
.Lmx_pb2_5:
	v_cvt_pk_bf16_f32 v185, v182, v183
	global_store_dword v105, v185, s[76:77] offset:-1024 sc1
	v_lshlrev_b32_e32 v174, 16, v229
	v_and_b32_e32 v175, 0xffff0000, v229
	v_lshlrev_b32_e32 v176, 16, v221
	v_and_b32_e32 v177, 0xffff0000, v221
	v_pk_add_f32 v[178:179], v[174:175], v[176:177] neg_lo:[0,1] neg_hi:[0,1]
	v_pk_add_f32 v[172:173], v[172:173], v[178:179]
	s_cmp_eq_u32 s64, 0
	s_cbranch_scc1 .Lmx_ps2_6
	v_pk_fma_f32 v[182:183], v[172:173], s[72:73], v[174:175] neg_lo:[0,0,1] neg_hi:[0,0,1]
; __device__ __forceinline__ unsigned pk2(float lo, float hi) { f32x2v v = {lo, hi}; b16x2v b = __builtin_convertvector(v, b16x2v); return __builtin_bit_cast(unsigned, b); }
; __device__ __forceinline__ f32x2v bf2(unsigned v) { return (f32x2v){bflo(v), bfhi(v)}; }
; template <int W>
; __device__ __forceinline__ void pool_prompt_w(const unsigned (&pin)[31], int t0, unsigned* dst  ) {
;     ...
;     for (int i = 0; i < W; ++i) s = s + bf2(pin[15 - i]);
; #pragma unroll
;     for (int t = 0; t < 16; ++t) {
;         if (t > 0) s = s + (bf2(pin[15 + t]) - bf2(pin[15 + t - W]));
;         const float cnt = (float)min(t0 + t + 1, W); const f32x2v cur = bf2(pin[15 + t]);
;         dst[(size_t)t * 512] = pk2(s.x / cnt - cur.x, s.y / cnt - cur.y);
.Lmx_pb2_6:
	v_cvt_pk_bf16_f32 v186, v182, v183
	global_store_dword v105, v186, s[76:77] offset:1024 sc1
	v_lshlrev_b32_e32 v174, 16, v230
	v_and_b32_e32 v175, 0xffff0000, v230
	v_lshlrev_b32_e32 v176, 16, v222
	v_and_b32_e32 v177, 0xffff0000, v222
	v_pk_add_f32 v[178:179], v[174:175], v[176:177] neg_lo:[0,1] neg_hi:[0,1]
	v_pk_add_f32 v[172:173], v[172:173], v[178:179]
	v_pk_fma_f32 v[182:183], v[172:173], s[72:73], v[174:175] neg_lo:[0,0,1] neg_hi:[0,0,1]
	v_cvt_pk_bf16_f32 v187, v182, v183
	global_store_dword v105, v187, s[76:77] offset:3072 sc1
	v_lshlrev_b32_e32 v174, 16, v231
	v_and_b32_e32 v175, 0xffff0000, v231
	v_lshlrev_b32_e32 v176, 16, v223
	v_and_b32_e32 v177, 0xffff0000, v223
	v_pk_add_f32 v[178:179], v[174:175], v[176:177] neg_lo:[0,1] neg_hi:[0,1]
	v_pk_add_f32 v[172:173], v[172:173], v[178:179]
	v_pk_fma_f32 v[182:183], v[172:173], s[72:73], v[174:175] neg_lo:[0,0,1] neg_hi:[0,0,1]
	v_cvt_pk_bf16_f32 v184, v182, v183
	s_add_u32 s76, s76, 0x2000
	s_addc_u32 s77, s77, 0
	s_waitcnt vmcnt(40)
	global_store_dword v105, v184, s[76:77] offset:-3072 sc1
	v_lshlrev_b32_e32 v174, 16, v232
	v_and_b32_e32 v175, 0xffff0000, v232
	v_lshlrev_b32_e32 v176, 16, v224
	v_and_b32_e32 v177, 0xffff0000, v224
	v_pk_add_f32 v[178:179], v[174:175], v[176:177] neg_lo:[0,1] neg_hi:[0,1]
	v_pk_add_f32 v[172:173], v[172:173], v[178:179]
	v_pk_fma_f32 v[182:183], v[172:173], s[72:73], v[174:175] neg_lo:[0,0,1] neg_hi:[0,0,1]
	v_cvt_pk_bf16_f32 v185, v182, v183
	global_store_dword v105, v185, s[76:77] offset:-1024 sc1
	v_lshlrev_b32_e32 v174, 16, v233
	v_and_b32_e32 v175, 0xffff0000, v233
	v_lshlrev_b32_e32 v176, 16, v225
	v_and_b32_e32 v177, 0xffff0000, v225
	v_pk_add_f32 v[178:179], v[174:175], v[176:177] neg_lo:[0,1] neg_hi:[0,1]
	v_pk_add_f32 v[172:173], v[172:173], v[178:179]
	v_pk_fma_f32 v[182:183], v[172:173], s[72:73], v[174:175] neg_lo:[0,0,1] neg_hi:[0,0,1]
	v_cvt_pk_bf16_f32 v186, v182, v183
	global_store_dword v105, v186, s[76:77] offset:1024 sc1
	v_lshlrev_b32_e32 v174, 16, v234
	v_and_b32_e32 v175, 0xffff0000, v234
	v_lshlrev_b32_e32 v176, 16, v226
	v_and_b32_e32 v177, 0xffff0000, v226
	v_pk_add_f32 v[178:179], v[174:175], v[176:177] neg_lo:[0,1] neg_hi:[0,1]
	v_pk_add_f32 v[172:173], v[172:173], v[178:179]
	v_pk_fma_f32 v[182:183], v[172:173], s[72:73], v[174:175] neg_lo:[0,0,1] neg_hi:[0,0,1]
	v_cvt_pk_bf16_f32 v187, v182, v183
	global_store_dword v105, v187, s[76:77] offset:3072 sc1
	v_lshlrev_b32_e32 v174, 16, v235
	v_and_b32_e32 v175, 0xffff0000, v235
	v_lshlrev_b32_e32 v176, 16, v227
	v_and_b32_e32 v177, 0xffff0000, v227
	v_pk_add_f32 v[178:179], v[174:175], v[176:177] neg_lo:[0,1] neg_hi:[0,1]
	v_pk_add_f32 v[172:173], v[172:173], v[178:179]
	v_pk_fma_f32 v[182:183], v[172:173], s[72:73], v[174:175] neg_lo:[0,0,1] neg_hi:[0,0,1]
	v_cvt_pk_bf16_f32 v184, v182, v183
	s_add_u32 s76, s76, 0x2000
	s_addc_u32 s77, s77, 0
	global_store_dword v105, v184, s[76:77] offset:-3072 sc1
	v_lshlrev_b32_e32 v174, 16, v236
	v_and_b32_e32 v175, 0xffff0000, v236
	v_lshlrev_b32_e32 v176, 16, v228
	v_and_b32_e32 v177, 0xffff0000, v228
	v_pk_add_f32 v[178:179], v[174:175], v[176:177] neg_lo:[0,1] neg_hi:[0,1]
	v_pk_add_f32 v[172:173], v[172:173], v[178:179]
	v_pk_fma_f32 v[182:183], v[172:173], s[72:73], v[174:175] neg_lo:[0,0,1] neg_hi:[0,0,1]
	v_cvt_pk_bf16_f32 v185, v182, v183
	global_store_dword v105, v185, s[76:77] offset:-1024 sc1
	v_lshlrev_b32_e32 v174, 16, v237
	v_and_b32_e32 v175, 0xffff0000, v237
	v_lshlrev_b32_e32 v176, 16, v229
	v_and_b32_e32 v177, 0xffff0000, v229
	v_pk_add_f32 v[178:179], v[174:175], v[176:177] neg_lo:[0,1] neg_hi:[0,1]
	v_pk_add_f32 v[172:173], v[172:173], v[178:179]
	v_pk_fma_f32 v[182:183], v[172:173], s[72:73], v[174:175] neg_lo:[0,0,1] neg_hi:[0,0,1]
	v_cvt_pk_bf16_f32 v186, v182, v183
	global_store_dword v105, v186, s[76:77] offset:1024 sc1
	v_lshlrev_b32_e32 v174, 16, v238
	v_and_b32_e32 v175, 0xffff0000, v238
	v_lshlrev_b32_e32 v176, 16, v230
	v_and_b32_e32 v177, 0xffff0000, v230
	v_pk_add_f32 v[178:179], v[174:175], v[176:177] neg_lo:[0,1] neg_hi:[0,1]
	v_pk_add_f32 v[172:173], v[172:173], v[178:179]
	v_pk_fma_f32 v[182:183], v[172:173], s[72:73], v[174:175] neg_lo:[0,0,1] neg_hi:[0,0,1]
	v_cvt_pk_bf16_f32 v187, v182, v183
	global_store_dword v105, v187, s[76:77] offset:3072 sc1
	s_branch .Lmx_pool_done

; __device__ __forceinline__ unsigned pk2(float lo, float hi) { f32x2v v = {lo, hi}; b16x2v b = __builtin_convertvector(v, b16x2v); return __builtin_bit_cast(unsigned, b); }
; __device__ __forceinline__ f32x2v bf2(unsigned v) { return (f32x2v){bflo(v), bfhi(v)}; }
; template <int W>
; __device__ __forceinline__ void pool_prompt_w(const unsigned (&pin)[31], int t0, unsigned* dst  ) {
;     ...
;     for (int i = 0; i < W; ++i) s = s + bf2(pin[15 - i]);
; #pragma unroll
;     for (int t = 0; t < 16; ++t) {
;         if (t > 0) s = s + (bf2(pin[15 + t]) - bf2(pin[15 + t - W]));
;         const float cnt = (float)min(t0 + t + 1, W); const f32x2v cur = bf2(pin[15 + t]);
;         dst[(size_t)t * 512] = pk2(s.x / cnt - cur.x, s.y / cnt - cur.y);
.Lmx_pb3_0:
	v_cvt_pk_bf16_f32 v184, v182, v183
	global_store_dword v105, v184, s[76:77] offset:-3072 sc1
	v_lshlrev_b32_e32 v174, 16, v224
	v_and_b32_e32 v175, 0xffff0000, v224
	v_lshlrev_b32_e32 v176, 16, v208
	v_and_b32_e32 v177, 0xffff0000, v208
	v_pk_add_f32 v[178:179], v[174:175], v[176:177] neg_lo:[0,1] neg_hi:[0,1]
	v_pk_add_f32 v[172:173], v[172:173], v[178:179]
	s_cmp_eq_u32 s64, 0
	s_cbranch_scc1 .Lmx_ps3_1
	v_pk_fma_f32 v[182:183], v[172:173], s[72:73], v[174:175] neg_lo:[0,0,1] neg_hi:[0,0,1]
.Lmx_pb3_1:
	v_cvt_pk_bf16_f32 v185, v182, v183
	global_store_dword v105, v185, s[76:77] offset:-1024 sc1
	v_lshlrev_b32_e32 v174, 16, v225
	v_and_b32_e32 v175, 0xffff0000, v225
	v_lshlrev_b32_e32 v176, 16, v209
	v_and_b32_e32 v177, 0xffff0000, v209
	v_pk_add_f32 v[178:179], v[174:175], v[176:177] neg_lo:[0,1] neg_hi:[0,1]
	v_pk_add_f32 v[172:173], v[172:173], v[178:179]
	s_cmp_eq_u32 s64, 0
	s_cbranch_scc1 .Lmx_ps3_2
	v_pk_fma_f32 v[182:183], v[172:173], s[72:73], v[174:175] neg_lo:[0,0,1] neg_hi:[0,0,1]
.Lmx_pb3_2:
	v_cvt_pk_bf16_f32 v186, v182, v183
	global_store_dword v105, v186, s[76:77] offset:1024 sc1
	v_lshlrev_b32_e32 v174, 16, v226
	v_and_b32_e32 v175, 0xffff0000, v226
	v_lshlrev_b32_e32 v176, 16, v210
	v_and_b32_e32 v177, 0xffff0000, v210
	v_pk_add_f32 v[178:179], v[174:175], v[176:177] neg_lo:[0,1] neg_hi:[0,1]
	v_pk_add_f32 v[172:173], v[172:173], v[178:179]
	s_cmp_eq_u32 s64, 0
	s_cbranch_scc1 .Lmx_ps3_3
	v_pk_fma_f32 v[182:183], v[172:173], s[72:73], v[174:175] neg_lo:[0,0,1] neg_hi:[0,0,1]
.Lmx_pb3_3:
	v_cvt_pk_bf16_f32 v187, v182, v183
	global_store_dword v105, v187, s[76:77] offset:3072 sc1
	v_lshlrev_b32_e32 v174, 16, v227
	v_and_b32_e32 v175, 0xffff0000, v227
	v_lshlrev_b32_e32 v176, 16, v211
	v_and_b32_e32 v177, 0xffff0000, v211
	v_pk_add_f32 v[178:179], v[174:175], v[176:177] neg_lo:[0,1] neg_hi:[0,1]
	v_pk_add_f32 v[172:173], v[172:173], v[178:179]
	s_cmp_eq_u32 s64, 0
	s_cbranch_scc1 .Lmx_ps3_4
	v_pk_fma_f32 v[182:183], v[172:173], s[72:73], v[174:175] neg_lo:[0,0,1] neg_hi:[0,0,1]
.Lmx_pb3_4:
	v_cvt_pk_bf16_f32 v184, v182, v183
	s_add_u32 s76, s76, 0x2000
	s_addc_u32 s77, s77, 0
	global_store_dword v105, v184, s[76:77] offset:-3072 sc1
	v_lshlrev_b32_e32 v174, 16, v228
	v_and_b32_e32 v175, 0xffff0000, v228
	v_lshlrev_b32_e32 v176, 16, v212
	v_and_b32_e32 v177, 0xffff0000, v212
	v_pk_add_f32 v[178:179], v[174:175], v[176:177] neg_lo:[0,1] neg_hi:[0,1]
	v_pk_add_f32 v[172:173], v[172:173], v[178:179]
	s_cmp_eq_u32 s64, 0
	s_cbranch_scc1 .Lmx_ps3_5
	v_pk_fma_f32 v[182:183], v[172:173], s[72:73], v[174:175] neg_lo:[0,0,1] neg_hi:[0,0,1]
.Lmx_pb3_5:
	v_cvt_pk_bf16_f32 v185, v182, v183
	global_store_dword v105, v185, s[76:77] offset:-1024 sc1
	v_lshlrev_b32_e32 v174, 16, v229
	v_and_b32_e32 v175, 0xffff0000, v229
	v_lshlrev_b32_e32 v176, 16, v213
	v_and_b32_e32 v177, 0xffff0000, v213
	v_pk_add_f32 v[178:179], v[174:175], v[176:177] neg_lo:[0,1] neg_hi:[0,1]
	v_pk_add_f32 v[172:173], v[172:173], v[178:179]
	s_cmp_eq_u32 s64, 0
	s_cbranch_scc1 .Lmx_ps3_6
	v_pk_fma_f32 v[182:183], v[172:173], s[72:73], v[174:175] neg_lo:[0,0,1] neg_hi:[0,0,1]
.Lmx_pb3_6:
	v_cvt_pk_bf16_f32 v186, v182, v183
	global_store_dword v105, v186, s[76:77] offset:1024 sc1
	v_lshlrev_b32_e32 v174, 16, v230
	v_and_b32_e32 v175, 0xffff0000, v230
	v_lshlrev_b32_e32 v176, 16, v214
	v_and_b32_e32 v177, 0xffff0000, v214
	v_pk_add_f32 v[178:179], v[174:175], v[176:177] neg_lo:[0,1] neg_hi:[0,1]
	v_pk_add_f32 v[172:173], v[172:173], v[178:179]
	s_cmp_eq_u32 s64, 0
	s_cbranch_scc1 .Lmx_ps3_7
	v_pk_fma_f32 v[182:183], v[172:173], s[72:73], v[174:175] neg_lo:[0,0,1] neg_hi:[0,0,1]
.Lmx_pb3_7:
	v_cvt_pk_bf16_f32 v187, v182, v183
	global_store_dword v105, v187, s[76:77] offset:3072 sc1
	v_lshlrev_b32_e32 v174, 16, v231
	v_and_b32_e32 v175, 0xffff0000, v231
	v_lshlrev_b32_e32 v176, 16, v215
	v_and_b32_e32 v177, 0xffff0000, v215
	v_pk_add_f32 v[178:179], v[174:175], v[176:177] neg_lo:[0,1] neg_hi:[0,1]
	v_pk_add_f32 v[172:173], v[172:173], v[178:179]
	s_cmp_eq_u32 s64, 0
	s_cbranch_scc1 .Lmx_ps3_8
	v_pk_fma_f32 v[182:183], v[172:173], s[72:73], v[174:175] neg_lo:[0,0,1] neg_hi:[0,0,1]
; __device__ __forceinline__ unsigned pk2(float lo, float hi) { f32x2v v = {lo, hi}; b16x2v b = __builtin_convertvector(v, b16x2v); return __builtin_bit_cast(unsigned, b); }
; __device__ __forceinline__ f32x2v bf2(unsigned v) { return (f32x2v){bflo(v), bfhi(v)}; }
; template <int W>
; __device__ __forceinline__ void pool_prompt_w(const unsigned (&pin)[31], int t0, unsigned* dst  ) {
;     ...
;     for (int i = 0; i < W; ++i) s = s + bf2(pin[15 - i]);
; #pragma unroll
;     for (int t = 0; t < 16; ++t) {
;         if (t > 0) s = s + (bf2(pin[15 + t]) - bf2(pin[15 + t - W]));
;         const float cnt = (float)min(t0 + t + 1, W); const f32x2v cur = bf2(pin[15 + t]);
;         dst[(size_t)t * 512] = pk2(s.x / cnt - cur.x, s.y / cnt - cur.y);
.Lmx_pb3_8:
	v_cvt_pk_bf16_f32 v184, v182, v183
	s_add_u32 s76, s76, 0x2000
	s_addc_u32 s77, s77, 0
	s_waitcnt vmcnt(40)
	global_store_dword v105, v184, s[76:77] offset:-3072 sc1
	v_lshlrev_b32_e32 v174, 16, v232
	v_and_b32_e32 v175, 0xffff0000, v232
	v_lshlrev_b32_e32 v176, 16, v216
	v_and_b32_e32 v177, 0xffff0000, v216
	v_pk_add_f32 v[178:179], v[174:175], v[176:177] neg_lo:[0,1] neg_hi:[0,1]
	v_pk_add_f32 v[172:173], v[172:173], v[178:179]
	s_cmp_eq_u32 s64, 0
	s_cbranch_scc1 .Lmx_ps3_9
	v_pk_fma_f32 v[182:183], v[172:173], s[72:73], v[174:175] neg_lo:[0,0,1] neg_hi:[0,0,1]
.Lmx_pb3_9:
	v_cvt_pk_bf16_f32 v185, v182, v183
	global_store_dword v105, v185, s[76:77] offset:-1024 sc1
	v_lshlrev_b32_e32 v174, 16, v233
	v_and_b32_e32 v175, 0xffff0000, v233
	v_lshlrev_b32_e32 v176, 16, v217
	v_and_b32_e32 v177, 0xffff0000, v217
	v_pk_add_f32 v[178:179], v[174:175], v[176:177] neg_lo:[0,1] neg_hi:[0,1]
	v_pk_add_f32 v[172:173], v[172:173], v[178:179]
	s_cmp_eq_u32 s64, 0
	s_cbranch_scc1 .Lmx_ps3_10
	v_pk_fma_f32 v[182:183], v[172:173], s[72:73], v[174:175] neg_lo:[0,0,1] neg_hi:[0,0,1]
.Lmx_pb3_10:
	v_cvt_pk_bf16_f32 v186, v182, v183
	global_store_dword v105, v186, s[76:77] offset:1024 sc1
	v_lshlrev_b32_e32 v174, 16, v234
	v_and_b32_e32 v175, 0xffff0000, v234
	v_lshlrev_b32_e32 v176, 16, v218
	v_and_b32_e32 v177, 0xffff0000, v218
	v_pk_add_f32 v[178:179], v[174:175], v[176:177] neg_lo:[0,1] neg_hi:[0,1]
	v_pk_add_f32 v[172:173], v[172:173], v[178:179]
	s_cmp_eq_u32 s64, 0
	s_cbranch_scc1 .Lmx_ps3_11
	v_pk_fma_f32 v[182:183], v[172:173], s[72:73], v[174:175] neg_lo:[0,0,1] neg_hi:[0,0,1]
.Lmx_pb3_11:
	v_cvt_pk_bf16_f32 v187, v182, v183
	global_store_dword v105, v187, s[76:77] offset:3072 sc1
	v_lshlrev_b32_e32 v174, 16, v235
	v_and_b32_e32 v175, 0xffff0000, v235
	v_lshlrev_b32_e32 v176, 16, v219
	v_and_b32_e32 v177, 0xffff0000, v219
	v_pk_add_f32 v[178:179], v[174:175], v[176:177] neg_lo:[0,1] neg_hi:[0,1]
	v_pk_add_f32 v[172:173], v[172:173], v[178:179]
	s_cmp_eq_u32 s64, 0
	s_cbranch_scc1 .Lmx_ps3_12
	v_pk_fma_f32 v[182:183], v[172:173], s[72:73], v[174:175] neg_lo:[0,0,1] neg_hi:[0,0,1]
.Lmx_pb3_12:
	v_cvt_pk_bf16_f32 v184, v182, v183
	s_add_u32 s76, s76, 0x2000
	s_addc_u32 s77, s77, 0
	global_store_dword v105, v184, s[76:77] offset:-3072 sc1
	v_lshlrev_b32_e32 v174, 16, v236
	v_and_b32_e32 v175, 0xffff0000, v236
	v_lshlrev_b32_e32 v176, 16, v220
	v_and_b32_e32 v177, 0xffff0000, v220
	v_pk_add_f32 v[178:179], v[174:175], v[176:177] neg_lo:[0,1] neg_hi:[0,1]
	v_pk_add_f32 v[172:173], v[172:173], v[178:179]
	s_cmp_eq_u32 s64, 0
	s_cbranch_scc1 .Lmx_ps3_13
	v_pk_fma_f32 v[182:183], v[172:173], s[72:73], v[174:175] neg_lo:[0,0,1] neg_hi:[0,0,1]
.Lmx_pb3_13:
	v_cvt_pk_bf16_f32 v185, v182, v183
	global_store_dword v105, v185, s[76:77] offset:-1024 sc1
	v_lshlrev_b32_e32 v174, 16, v237
	v_and_b32_e32 v175, 0xffff0000, v237
	v_lshlrev_b32_e32 v176, 16, v221
	v_and_b32_e32 v177, 0xffff0000, v221
	v_pk_add_f32 v[178:179], v[174:175], v[176:177] neg_lo:[0,1] neg_hi:[0,1]
	v_pk_add_f32 v[172:173], v[172:173], v[178:179]
	s_cmp_eq_u32 s64, 0
	s_cbranch_scc1 .Lmx_ps3_14
	v_pk_fma_f32 v[182:183], v[172:173], s[72:73], v[174:175] neg_lo:[0,0,1] neg_hi:[0,0,1]
.Lmx_pb3_14:
	v_cvt_pk_bf16_f32 v186, v182, v183
	global_store_dword v105, v186, s[76:77] offset:1024 sc1
	v_lshlrev_b32_e32 v174, 16, v238
	v_and_b32_e32 v175, 0xffff0000, v238
	v_lshlrev_b32_e32 v176, 16, v222
	v_and_b32_e32 v177, 0xffff0000, v222
	v_pk_add_f32 v[178:179], v[174:175], v[176:177] neg_lo:[0,1] neg_hi:[0,1]
	v_pk_add_f32 v[172:173], v[172:173], v[178:179]
	v_pk_fma_f32 v[182:183], v[172:173], s[72:73], v[174:175] neg_lo:[0,0,1] neg_hi:[0,0,1]
	v_cvt_pk_bf16_f32 v187, v182, v183
	global_store_dword v105, v187, s[76:77] offset:3072 sc1
	s_branch .Lmx_pool_done

; __device__ __forceinline__ f32x2v bf2(unsigned v) { return (f32x2v){bflo(v), bfhi(v)}; }
; __device__ __forceinline__ void mixer_prompt_run(const Args& p, int run, int c2) {
;     ...
;             for (int t = 0; t < 8; ++t) a[t] = cb;
; #pragma unroll
;             for (int i = 0; i < 38; ++i) {
;                 const int ti = t0 + 8 * hh - 30 + i; unsigned v = U32[(rowb + (ti >= 0 ? ti : 0)) * 256 + c2]; v = (ti >= 0) ? v : 0u; const f32x2v x = bf2(v);
; #pragma unroll
;                 for (int t = 0; t < 8; ++t) { const int j = i - t; if (j >= 0 && j <= 30) a[t] = w[j] * x + a[t]; }
;                 if (i == 18) asm volatile("" ::: "memory");
;             }
.Lmx_b29:
	v_lshlrev_b32_e32 v98, 16, v222
	v_and_b32_e32 v99, 0xffff0000, v222
	v_pk_fma_f32 v[172:173], v[168:169], v[98:99], v[172:173]
	v_pk_fma_f32 v[174:175], v[162:163], v[98:99], v[174:175]
	v_pk_fma_f32 v[176:177], v[160:161], v[98:99], v[176:177]
	v_pk_fma_f32 v[178:179], v[158:159], v[98:99], v[178:179]
	v_pk_fma_f32 v[180:181], v[156:157], v[98:99], v[180:181]
	v_pk_fma_f32 v[182:183], v[154:155], v[98:99], v[182:183]
	v_pk_fma_f32 v[184:185], v[152:153], v[98:99], v[184:185]
	v_pk_fma_f32 v[186:187], v[150:151], v[98:99], v[186:187]
	v_pk_fma_f32 v[188:189], v[148:149], v[98:99], v[188:189]
	v_pk_fma_f32 v[190:191], v[146:147], v[98:99], v[190:191]
	v_pk_fma_f32 v[78:79], v[144:145], v[98:99], v[78:79]
	v_pk_fma_f32 v[80:81], v[142:143], v[98:99], v[80:81]
	v_pk_fma_f32 v[82:83], v[140:141], v[98:99], v[82:83]
	v_pk_fma_f32 v[84:85], v[138:139], v[98:99], v[84:85]
	v_pk_fma_f32 v[86:87], v[136:137], v[98:99], v[86:87]
	v_pk_fma_f32 v[88:89], v[134:135], v[98:99], v[88:89]
	s_waitcnt vmcnt(15)
	v_lshlrev_b32_e32 v96, 16, v223
	v_and_b32_e32 v97, 0xffff0000, v223
	v_pk_fma_f32 v[172:173], v[170:171], v[96:97], v[172:173]
	v_pk_fma_f32 v[174:175], v[168:169], v[96:97], v[174:175]
	v_pk_fma_f32 v[176:177], v[162:163], v[96:97], v[176:177]
	v_pk_fma_f32 v[178:179], v[160:161], v[96:97], v[178:179]
	v_pk_fma_f32 v[180:181], v[158:159], v[96:97], v[180:181]
	v_pk_fma_f32 v[182:183], v[156:157], v[96:97], v[182:183]
	v_pk_fma_f32 v[184:185], v[154:155], v[96:97], v[184:185]
	v_pk_fma_f32 v[186:187], v[152:153], v[96:97], v[186:187]
	v_pk_fma_f32 v[188:189], v[150:151], v[96:97], v[188:189]
	v_pk_fma_f32 v[190:191], v[148:149], v[96:97], v[190:191]
	v_pk_fma_f32 v[78:79], v[146:147], v[96:97], v[78:79]
	v_pk_fma_f32 v[80:81], v[144:145], v[96:97], v[80:81]
	v_pk_fma_f32 v[82:83], v[142:143], v[96:97], v[82:83]
	v_pk_fma_f32 v[84:85], v[140:141], v[96:97], v[84:85]
	v_pk_fma_f32 v[86:87], v[138:139], v[96:97], v[86:87]
	v_pk_fma_f32 v[88:89], v[136:137], v[96:97], v[88:89]
	s_waitcnt vmcnt(14)
	v_lshlrev_b32_e32 v98, 16, v224
	v_and_b32_e32 v99, 0xffff0000, v224
	v_pk_fma_f32 v[174:175], v[170:171], v[98:99], v[174:175]
	v_pk_fma_f32 v[176:177], v[168:169], v[98:99], v[176:177]
	v_pk_fma_f32 v[178:179], v[162:163], v[98:99], v[178:179]
	v_pk_fma_f32 v[180:181], v[160:161], v[98:99], v[180:181]
	v_pk_fma_f32 v[182:183], v[158:159], v[98:99], v[182:183]
	v_pk_fma_f32 v[184:185], v[156:157], v[98:99], v[184:185]
	v_pk_fma_f32 v[186:187], v[154:155], v[98:99], v[186:187]
	v_pk_fma_f32 v[188:189], v[152:153], v[98:99], v[188:189]
	v_pk_fma_f32 v[190:191], v[150:151], v[98:99], v[190:191]
	v_pk_fma_f32 v[78:79], v[148:149], v[98:99], v[78:79]
	v_pk_fma_f32 v[80:81], v[146:147], v[98:99], v[80:81]
	v_pk_fma_f32 v[82:83], v[144:145], v[98:99], v[82:83]
	v_pk_fma_f32 v[84:85], v[142:143], v[98:99], v[84:85]
	v_pk_fma_f32 v[86:87], v[140:141], v[98:99], v[86:87]
	v_pk_fma_f32 v[88:89], v[138:139], v[98:99], v[88:89]
	s_waitcnt vmcnt(13)
	v_lshlrev_b32_e32 v96, 16, v225
	v_and_b32_e32 v97, 0xffff0000, v225
	v_pk_fma_f32 v[176:177], v[170:171], v[96:97], v[176:177]
	v_pk_fma_f32 v[178:179], v[168:169], v[96:97], v[178:179]
	v_pk_fma_f32 v[180:181], v[162:163], v[96:97], v[180:181]
	v_pk_fma_f32 v[182:183], v[160:161], v[96:97], v[182:183]
	v_pk_fma_f32 v[184:185], v[158:159], v[96:97], v[184:185]
	v_pk_fma_f32 v[186:187], v[156:157], v[96:97], v[186:187]
	v_pk_fma_f32 v[188:189], v[154:155], v[96:97], v[188:189]
	v_pk_fma_f32 v[190:191], v[152:153], v[96:97], v[190:191]
	v_pk_fma_f32 v[78:79], v[150:151], v[96:97], v[78:79]
	v_pk_fma_f32 v[80:81], v[148:149], v[96:97], v[80:81]
	v_pk_fma_f32 v[82:83], v[146:147], v[96:97], v[82:83]
	v_pk_fma_f32 v[84:85], v[144:145], v[96:97], v[84:85]
	v_pk_fma_f32 v[86:87], v[142:143], v[96:97], v[86:87]
	v_pk_fma_f32 v[88:89], v[140:141], v[96:97], v[88:89]
	s_waitcnt vmcnt(12)
	v_lshlrev_b32_e32 v98, 16, v226
	v_and_b32_e32 v99, 0xffff0000, v226
	v_pk_fma_f32 v[178:179], v[170:171], v[98:99], v[178:179]
	v_pk_fma_f32 v[180:181], v[168:169], v[98:99], v[180:181]
	v_pk_fma_f32 v[182:183], v[162:163], v[98:99], v[182:183]
	v_pk_fma_f32 v[184:185], v[160:161], v[98:99], v[184:185]
	v_pk_fma_f32 v[186:187], v[158:159], v[98:99], v[186:187]
	v_pk_fma_f32 v[188:189], v[156:157], v[98:99], v[188:189]
	v_pk_fma_f32 v[190:191], v[154:155], v[98:99], v[190:191]
	v_pk_fma_f32 v[78:79], v[152:153], v[98:99], v[78:79]
	v_pk_fma_f32 v[80:81], v[150:151], v[98:99], v[80:81]
	v_pk_fma_f32 v[82:83], v[148:149], v[98:99], v[82:83]
	v_pk_fma_f32 v[84:85], v[146:147], v[98:99], v[84:85]
	v_pk_fma_f32 v[86:87], v[144:145], v[98:99], v[86:87]
	v_pk_fma_f32 v[88:89], v[142:143], v[98:99], v[88:89]
	s_waitcnt vmcnt(11)
	v_lshlrev_b32_e32 v96, 16, v227
	v_and_b32_e32 v97, 0xffff0000, v227
	v_pk_fma_f32 v[180:181], v[170:171], v[96:97], v[180:181]
	v_pk_fma_f32 v[182:183], v[168:169], v[96:97], v[182:183]
	v_pk_fma_f32 v[184:185], v[162:163], v[96:97], v[184:185]
	v_pk_fma_f32 v[186:187], v[160:161], v[96:97], v[186:187]
	v_pk_fma_f32 v[188:189], v[158:159], v[96:97], v[188:189]
	v_pk_fma_f32 v[190:191], v[156:157], v[96:97], v[190:191]
	v_pk_fma_f32 v[78:79], v[154:155], v[96:97], v[78:79]
	v_pk_fma_f32 v[80:81], v[152:153], v[96:97], v[80:81]
	v_pk_fma_f32 v[82:83], v[150:151], v[96:97], v[82:83]
	v_pk_fma_f32 v[84:85], v[148:149], v[96:97], v[84:85]
	v_pk_fma_f32 v[86:87], v[146:147], v[96:97], v[86:87]
	v_pk_fma_f32 v[88:89], v[144:145], v[96:97], v[88:89]
	s_waitcnt vmcnt(10)
; __device__ __forceinline__ f32x2v bf2(unsigned v) { return (f32x2v){bflo(v), bfhi(v)}; }
; __device__ __forceinline__ void mixer_prompt_run(const Args& p, int run, int c2) {
;     ...
;             for (int t = 0; t < 8; ++t) a[t] = cb;
; #pragma unroll
;             for (int i = 0; i < 38; ++i) {
;                 const int ti = t0 + 8 * hh - 30 + i; unsigned v = U32[(rowb + (ti >= 0 ? ti : 0)) * 256 + c2]; v = (ti >= 0) ? v : 0u; const f32x2v x = bf2(v);
; #pragma unroll
;                 for (int t = 0; t < 8; ++t) { const int j = i - t; if (j >= 0 && j <= 30) a[t] = w[j] * x + a[t]; }
;                 if (i == 18) asm volatile("" ::: "memory");
;             }
	v_lshlrev_b32_e32 v98, 16, v228
	v_and_b32_e32 v99, 0xffff0000, v228
	v_pk_fma_f32 v[182:183], v[170:171], v[98:99], v[182:183]
	v_pk_fma_f32 v[184:185], v[168:169], v[98:99], v[184:185]
	v_pk_fma_f32 v[186:187], v[162:163], v[98:99], v[186:187]
	v_pk_fma_f32 v[188:189], v[160:161], v[98:99], v[188:189]
	v_pk_fma_f32 v[190:191], v[158:159], v[98:99], v[190:191]
	v_pk_fma_f32 v[78:79], v[156:157], v[98:99], v[78:79]
	v_pk_fma_f32 v[80:81], v[154:155], v[98:99], v[80:81]
	v_pk_fma_f32 v[82:83], v[152:153], v[98:99], v[82:83]
	v_pk_fma_f32 v[84:85], v[150:151], v[98:99], v[84:85]
	v_pk_fma_f32 v[86:87], v[148:149], v[98:99], v[86:87]
	v_pk_fma_f32 v[88:89], v[146:147], v[98:99], v[88:89]
	s_waitcnt vmcnt(9)
	v_lshlrev_b32_e32 v96, 16, v229
	v_and_b32_e32 v97, 0xffff0000, v229
	v_pk_fma_f32 v[184:185], v[170:171], v[96:97], v[184:185]
	v_pk_fma_f32 v[186:187], v[168:169], v[96:97], v[186:187]
	v_pk_fma_f32 v[188:189], v[162:163], v[96:97], v[188:189]
	v_pk_fma_f32 v[190:191], v[160:161], v[96:97], v[190:191]
	v_pk_fma_f32 v[78:79], v[158:159], v[96:97], v[78:79]
	v_pk_fma_f32 v[80:81], v[156:157], v[96:97], v[80:81]
	v_pk_fma_f32 v[82:83], v[154:155], v[96:97], v[82:83]
	v_pk_fma_f32 v[84:85], v[152:153], v[96:97], v[84:85]
	v_pk_fma_f32 v[86:87], v[150:151], v[96:97], v[86:87]
	v_pk_fma_f32 v[88:89], v[148:149], v[96:97], v[88:89]
	s_waitcnt vmcnt(8)
	v_lshlrev_b32_e32 v98, 16, v230
	v_and_b32_e32 v99, 0xffff0000, v230
	v_pk_fma_f32 v[186:187], v[170:171], v[98:99], v[186:187]
	v_pk_fma_f32 v[188:189], v[168:169], v[98:99], v[188:189]
	v_pk_fma_f32 v[190:191], v[162:163], v[98:99], v[190:191]
	v_pk_fma_f32 v[78:79], v[160:161], v[98:99], v[78:79]
	v_pk_fma_f32 v[80:81], v[158:159], v[98:99], v[80:81]
	v_pk_fma_f32 v[82:83], v[156:157], v[98:99], v[82:83]
	v_pk_fma_f32 v[84:85], v[154:155], v[98:99], v[84:85]
	v_pk_fma_f32 v[86:87], v[152:153], v[98:99], v[86:87]
	v_pk_fma_f32 v[88:89], v[150:151], v[98:99], v[88:89]
	s_waitcnt vmcnt(7)
	v_lshlrev_b32_e32 v96, 16, v231
	v_and_b32_e32 v97, 0xffff0000, v231
	v_pk_fma_f32 v[188:189], v[170:171], v[96:97], v[188:189]
	v_pk_fma_f32 v[190:191], v[168:169], v[96:97], v[190:191]
	v_pk_fma_f32 v[78:79], v[162:163], v[96:97], v[78:79]
	v_pk_fma_f32 v[80:81], v[160:161], v[96:97], v[80:81]
	v_pk_fma_f32 v[82:83], v[158:159], v[96:97], v[82:83]
	v_pk_fma_f32 v[84:85], v[156:157], v[96:97], v[84:85]
	v_pk_fma_f32 v[86:87], v[154:155], v[96:97], v[86:87]
	v_pk_fma_f32 v[88:89], v[152:153], v[96:97], v[88:89]
	s_waitcnt vmcnt(6)
	v_lshlrev_b32_e32 v98, 16, v232
	v_and_b32_e32 v99, 0xffff0000, v232
	v_pk_fma_f32 v[190:191], v[170:171], v[98:99], v[190:191]
	v_pk_fma_f32 v[78:79], v[168:169], v[98:99], v[78:79]
	v_pk_fma_f32 v[80:81], v[162:163], v[98:99], v[80:81]
	v_pk_fma_f32 v[82:83], v[160:161], v[98:99], v[82:83]
	v_pk_fma_f32 v[84:85], v[158:159], v[98:99], v[84:85]
	v_pk_fma_f32 v[86:87], v[156:157], v[98:99], v[86:87]
	v_pk_fma_f32 v[88:89], v[154:155], v[98:99], v[88:89]
	s_waitcnt vmcnt(5)
	v_lshlrev_b32_e32 v96, 16, v233
	v_and_b32_e32 v97, 0xffff0000, v233
	v_pk_fma_f32 v[78:79], v[170:171], v[96:97], v[78:79]
	v_pk_fma_f32 v[80:81], v[168:169], v[96:97], v[80:81]
	v_pk_fma_f32 v[82:83], v[162:163], v[96:97], v[82:83]
	v_pk_fma_f32 v[84:85], v[160:161], v[96:97], v[84:85]
	v_pk_fma_f32 v[86:87], v[158:159], v[96:97], v[86:87]
	v_pk_fma_f32 v[88:89], v[156:157], v[96:97], v[88:89]
	s_waitcnt vmcnt(4)
	v_lshlrev_b32_e32 v98, 16, v234
	v_and_b32_e32 v99, 0xffff0000, v234
	v_pk_fma_f32 v[80:81], v[170:171], v[98:99], v[80:81]
	v_pk_fma_f32 v[82:83], v[168:169], v[98:99], v[82:83]
	v_pk_fma_f32 v[84:85], v[162:163], v[98:99], v[84:85]
	v_pk_fma_f32 v[86:87], v[160:161], v[98:99], v[86:87]
	v_pk_fma_f32 v[88:89], v[158:159], v[98:99], v[88:89]
	s_waitcnt vmcnt(3)
	v_lshlrev_b32_e32 v96, 16, v235
	v_and_b32_e32 v97, 0xffff0000, v235
	v_pk_fma_f32 v[82:83], v[170:171], v[96:97], v[82:83]
	v_pk_fma_f32 v[84:85], v[168:169], v[96:97], v[84:85]
	v_pk_fma_f32 v[86:87], v[162:163], v[96:97], v[86:87]
	v_pk_fma_f32 v[88:89], v[160:161], v[96:97], v[88:89]
	s_waitcnt vmcnt(2)
	v_lshlrev_b32_e32 v98, 16, v236
	v_and_b32_e32 v99, 0xffff0000, v236
	v_pk_fma_f32 v[84:85], v[170:171], v[98:99], v[84:85]
	v_pk_fma_f32 v[86:87], v[168:169], v[98:99], v[86:87]
	v_pk_fma_f32 v[88:89], v[162:163], v[98:99], v[88:89]
	s_waitcnt vmcnt(1)
	v_lshlrev_b32_e32 v96, 16, v237
	v_and_b32_e32 v97, 0xffff0000, v237
	v_pk_fma_f32 v[86:87], v[170:171], v[96:97], v[86:87]
	v_pk_fma_f32 v[88:89], v[168:169], v[96:97], v[88:89]
	s_waitcnt vmcnt(0)
; template <int CTRL> __device__ __forceinline__ float dpp_mov(float v) { return __builtin_bit_cast(float, __builtin_amdgcn_update_dpp(0, __builtin_bit_cast(int, v), CTRL, 0xf, 0xf, true)); }
; __device__ __forceinline__ float half_wave_sum(float v) {
;     v += dpp_mov<0xB1>(v);
;     v += dpp_mov<0x4E>(v);
;     v += dpp_mov<0x141>(v);
;     v += dpp_mov<0x140>(v);
;     v += __shfl_xor(v, 16);
;     return v;
; }
; __device__ __forceinline__ void gn_swish_store(float v0, float v1, f32x2v gg, f32x2v gb, unsigned* dst) {
;     const float mean = half_wave_sum(v0 + v1) * (1.0f / 64.0f); const float d0 = v0 - mean, d1 = v1 - mean;
;     const float rstd = rsqrtf(half_wave_sum(d0 * d0 + d1 * d1) * (1.0f / 64.0f) + LN_EPS);
	v_lshlrev_b32_e32 v98, 16, v238
	v_and_b32_e32 v99, 0xffff0000, v238
	v_pk_fma_f32 v[88:89], v[170:171], v[98:99], v[88:89]
	v_add_f32_e32 v194, v172, v173
	v_add_f32_e32 v198, v174, v175
	v_add_f32_e32 v202, v176, v177
	v_add_f32_e32 v206, v178, v179
	v_add_f32_e32 v210, v180, v181
	v_add_f32_e32 v214, v182, v183
	v_add_f32_e32 v218, v184, v185
	v_add_f32_e32 v222, v186, v187
	v_add_f32_dpp v194, v194, v194 quad_perm:[1,0,3,2] row_mask:0xf bank_mask:0xf bound_ctrl:1
	v_add_f32_dpp v198, v198, v198 quad_perm:[1,0,3,2] row_mask:0xf bank_mask:0xf bound_ctrl:1
	v_add_f32_dpp v202, v202, v202 quad_perm:[1,0,3,2] row_mask:0xf bank_mask:0xf bound_ctrl:1
	v_add_f32_dpp v206, v206, v206 quad_perm:[1,0,3,2] row_mask:0xf bank_mask:0xf bound_ctrl:1
	v_add_f32_dpp v210, v210, v210 quad_perm:[1,0,3,2] row_mask:0xf bank_mask:0xf bound_ctrl:1
	v_add_f32_dpp v214, v214, v214 quad_perm:[1,0,3,2] row_mask:0xf bank_mask:0xf bound_ctrl:1
	v_add_f32_dpp v218, v218, v218 quad_perm:[1,0,3,2] row_mask:0xf bank_mask:0xf bound_ctrl:1
	v_add_f32_dpp v222, v222, v222 quad_perm:[1,0,3,2] row_mask:0xf bank_mask:0xf bound_ctrl:1
	v_add_f32_dpp v194, v194, v194 quad_perm:[2,3,0,1] row_mask:0xf bank_mask:0xf bound_ctrl:1
	v_add_f32_dpp v198, v198, v198 quad_perm:[2,3,0,1] row_mask:0xf bank_mask:0xf bound_ctrl:1
	v_add_f32_dpp v202, v202, v202 quad_perm:[2,3,0,1] row_mask:0xf bank_mask:0xf bound_ctrl:1
	v_add_f32_dpp v206, v206, v206 quad_perm:[2,3,0,1] row_mask:0xf bank_mask:0xf bound_ctrl:1
	v_add_f32_dpp v210, v210, v210 quad_perm:[2,3,0,1] row_mask:0xf bank_mask:0xf bound_ctrl:1
	v_add_f32_dpp v214, v214, v214 quad_perm:[2,3,0,1] row_mask:0xf bank_mask:0xf bound_ctrl:1
	v_add_f32_dpp v218, v218, v218 quad_perm:[2,3,0,1] row_mask:0xf bank_mask:0xf bound_ctrl:1
	v_add_f32_dpp v222, v222, v222 quad_perm:[2,3,0,1] row_mask:0xf bank_mask:0xf bound_ctrl:1
	v_add_f32_dpp v194, v194, v194 row_half_mirror row_mask:0xf bank_mask:0xf bound_ctrl:1
	v_add_f32_dpp v198, v198, v198 row_half_mirror row_mask:0xf bank_mask:0xf bound_ctrl:1
	v_add_f32_dpp v202, v202, v202 row_half_mirror row_mask:0xf bank_mask:0xf bound_ctrl:1
	v_add_f32_dpp v206, v206, v206 row_half_mirror row_mask:0xf bank_mask:0xf bound_ctrl:1
	v_add_f32_dpp v210, v210, v210 row_half_mirror row_mask:0xf bank_mask:0xf bound_ctrl:1
	v_add_f32_dpp v214, v214, v214 row_half_mirror row_mask:0xf bank_mask:0xf bound_ctrl:1
	v_add_f32_dpp v218, v218, v218 row_half_mirror row_mask:0xf bank_mask:0xf bound_ctrl:1
	v_add_f32_dpp v222, v222, v222 row_half_mirror row_mask:0xf bank_mask:0xf bound_ctrl:1
	v_add_f32_dpp v194, v194, v194 row_mirror row_mask:0xf bank_mask:0xf bound_ctrl:1
	v_add_f32_dpp v198, v198, v198 row_mirror row_mask:0xf bank_mask:0xf bound_ctrl:1
	v_add_f32_dpp v202, v202, v202 row_mirror row_mask:0xf bank_mask:0xf bound_ctrl:1
	v_add_f32_dpp v206, v206, v206 row_mirror row_mask:0xf bank_mask:0xf bound_ctrl:1
	v_add_f32_dpp v210, v210, v210 row_mirror row_mask:0xf bank_mask:0xf bound_ctrl:1
	v_add_f32_dpp v214, v214, v214 row_mirror row_mask:0xf bank_mask:0xf bound_ctrl:1
	v_add_f32_dpp v218, v218, v218 row_mirror row_mask:0xf bank_mask:0xf bound_ctrl:1
	v_add_f32_dpp v222, v222, v222 row_mirror row_mask:0xf bank_mask:0xf bound_ctrl:1
	ds_bpermute_b32 v195, v239, v194
	ds_bpermute_b32 v199, v239, v198
	ds_bpermute_b32 v203, v239, v202
	ds_bpermute_b32 v207, v239, v206
	ds_bpermute_b32 v211, v239, v210
	ds_bpermute_b32 v215, v239, v214
	ds_bpermute_b32 v219, v239, v218
	ds_bpermute_b32 v223, v239, v222
	s_waitcnt lgkmcnt(7)
	v_add_f32_e32 v194, v194, v195
	s_waitcnt lgkmcnt(6)
	v_add_f32_e32 v198, v198, v199
	s_waitcnt lgkmcnt(5)
	v_add_f32_e32 v202, v202, v203
	s_waitcnt lgkmcnt(4)
	v_add_f32_e32 v206, v206, v207
	s_waitcnt lgkmcnt(3)
	v_add_f32_e32 v210, v210, v211
	s_waitcnt lgkmcnt(2)
	v_add_f32_e32 v214, v214, v215
	s_waitcnt lgkmcnt(1)
	v_add_f32_e32 v218, v218, v219
	s_waitcnt lgkmcnt(0)
	v_add_f32_e32 v222, v222, v223
	v_pk_fma_f32 v[172:173], v[194:195], s[78:79], v[172:173] op_sel_hi:[0,1,1]
	v_pk_fma_f32 v[174:175], v[198:199], s[78:79], v[174:175] op_sel_hi:[0,1,1]
	v_pk_fma_f32 v[176:177], v[202:203], s[78:79], v[176:177] op_sel_hi:[0,1,1]
	v_pk_fma_f32 v[178:179], v[206:207], s[78:79], v[178:179] op_sel_hi:[0,1,1]
	v_pk_fma_f32 v[180:181], v[210:211], s[78:79], v[180:181] op_sel_hi:[0,1,1]
	v_pk_fma_f32 v[182:183], v[214:215], s[78:79], v[182:183] op_sel_hi:[0,1,1]
	v_pk_fma_f32 v[184:185], v[218:219], s[78:79], v[184:185] op_sel_hi:[0,1,1]
	v_pk_fma_f32 v[186:187], v[222:223], s[78:79], v[186:187] op_sel_hi:[0,1,1]
	v_pk_mul_f32 v[196:197], v[172:173], v[172:173]
	v_pk_mul_f32 v[200:201], v[174:175], v[174:175]
	v_pk_mul_f32 v[204:205], v[176:177], v[176:177]
	v_pk_mul_f32 v[208:209], v[178:179], v[178:179]
	v_pk_mul_f32 v[212:213], v[180:181], v[180:181]
	v_pk_mul_f32 v[216:217], v[182:183], v[182:183]
	v_pk_mul_f32 v[220:221], v[184:185], v[184:185]
	v_pk_mul_f32 v[224:225], v[186:187], v[186:187]
	v_add_f32_e32 v194, v196, v197
	v_add_f32_e32 v198, v200, v201
	v_add_f32_e32 v202, v204, v205
	v_add_f32_e32 v206, v208, v209
	v_add_f32_e32 v210, v212, v213
	v_add_f32_e32 v214, v216, v217
	v_add_f32_e32 v218, v220, v221
	v_add_f32_e32 v222, v224, v225
	v_add_f32_dpp v194, v194, v194 quad_perm:[1,0,3,2] row_mask:0xf bank_mask:0xf bound_ctrl:1
	v_add_f32_dpp v198, v198, v198 quad_perm:[1,0,3,2] row_mask:0xf bank_mask:0xf bound_ctrl:1
	v_add_f32_dpp v202, v202, v202 quad_perm:[1,0,3,2] row_mask:0xf bank_mask:0xf bound_ctrl:1
	v_add_f32_dpp v206, v206, v206 quad_perm:[1,0,3,2] row_mask:0xf bank_mask:0xf bound_ctrl:1
	v_add_f32_dpp v210, v210, v210 quad_perm:[1,0,3,2] row_mask:0xf bank_mask:0xf bound_ctrl:1
; __device__ __forceinline__ unsigned pk2(float lo, float hi) { f32x2v v = {lo, hi}; b16x2v b = __builtin_convertvector(v, b16x2v); return __builtin_bit_cast(unsigned, b); }
; __device__ __forceinline__ float fsigmoid(float x) { return __builtin_amdgcn_rcpf(1.0f + __expf(-x)); }
; __device__ __forceinline__ void gn_swish_store(float v0, float v1, f32x2v gg, f32x2v gb, unsigned* dst) {
;     const float mean = half_wave_sum(v0 + v1) * (1.0f / 64.0f); const float d0 = v0 - mean, d1 = v1 - mean;
;     const float rstd = rsqrtf(half_wave_sum(d0 * d0 + d1 * d1) * (1.0f / 64.0f) + LN_EPS);
;     float y0 = d0 * rstd * gg.x + gb.x, y1 = d1 * rstd * gg.y + gb.y;
;     y0 = y0 * fsigmoid(y0); y1 = y1 * fsigmoid(y1);
;     *dst = pk2(y0, y1);
	v_add_f32_dpp v214, v214, v214 quad_perm:[1,0,3,2] row_mask:0xf bank_mask:0xf bound_ctrl:1
	v_add_f32_dpp v218, v218, v218 quad_perm:[1,0,3,2] row_mask:0xf bank_mask:0xf bound_ctrl:1
	v_add_f32_dpp v222, v222, v222 quad_perm:[1,0,3,2] row_mask:0xf bank_mask:0xf bound_ctrl:1
	v_add_f32_dpp v194, v194, v194 quad_perm:[2,3,0,1] row_mask:0xf bank_mask:0xf bound_ctrl:1
	v_add_f32_dpp v198, v198, v198 quad_perm:[2,3,0,1] row_mask:0xf bank_mask:0xf bound_ctrl:1
	v_add_f32_dpp v202, v202, v202 quad_perm:[2,3,0,1] row_mask:0xf bank_mask:0xf bound_ctrl:1
	v_add_f32_dpp v206, v206, v206 quad_perm:[2,3,0,1] row_mask:0xf bank_mask:0xf bound_ctrl:1
	v_add_f32_dpp v210, v210, v210 quad_perm:[2,3,0,1] row_mask:0xf bank_mask:0xf bound_ctrl:1
	v_add_f32_dpp v214, v214, v214 quad_perm:[2,3,0,1] row_mask:0xf bank_mask:0xf bound_ctrl:1
	v_add_f32_dpp v218, v218, v218 quad_perm:[2,3,0,1] row_mask:0xf bank_mask:0xf bound_ctrl:1
	v_add_f32_dpp v222, v222, v222 quad_perm:[2,3,0,1] row_mask:0xf bank_mask:0xf bound_ctrl:1
	v_add_f32_dpp v194, v194, v194 row_half_mirror row_mask:0xf bank_mask:0xf bound_ctrl:1
	v_add_f32_dpp v198, v198, v198 row_half_mirror row_mask:0xf bank_mask:0xf bound_ctrl:1
	v_add_f32_dpp v202, v202, v202 row_half_mirror row_mask:0xf bank_mask:0xf bound_ctrl:1
	v_add_f32_dpp v206, v206, v206 row_half_mirror row_mask:0xf bank_mask:0xf bound_ctrl:1
	v_add_f32_dpp v210, v210, v210 row_half_mirror row_mask:0xf bank_mask:0xf bound_ctrl:1
	v_add_f32_dpp v214, v214, v214 row_half_mirror row_mask:0xf bank_mask:0xf bound_ctrl:1
	v_add_f32_dpp v218, v218, v218 row_half_mirror row_mask:0xf bank_mask:0xf bound_ctrl:1
	v_add_f32_dpp v222, v222, v222 row_half_mirror row_mask:0xf bank_mask:0xf bound_ctrl:1
	v_add_f32_dpp v194, v194, v194 row_mirror row_mask:0xf bank_mask:0xf bound_ctrl:1
	v_add_f32_dpp v198, v198, v198 row_mirror row_mask:0xf bank_mask:0xf bound_ctrl:1
	v_add_f32_dpp v202, v202, v202 row_mirror row_mask:0xf bank_mask:0xf bound_ctrl:1
	v_add_f32_dpp v206, v206, v206 row_mirror row_mask:0xf bank_mask:0xf bound_ctrl:1
	v_add_f32_dpp v210, v210, v210 row_mirror row_mask:0xf bank_mask:0xf bound_ctrl:1
	v_add_f32_dpp v214, v214, v214 row_mirror row_mask:0xf bank_mask:0xf bound_ctrl:1
	v_add_f32_dpp v218, v218, v218 row_mirror row_mask:0xf bank_mask:0xf bound_ctrl:1
	v_add_f32_dpp v222, v222, v222 row_mirror row_mask:0xf bank_mask:0xf bound_ctrl:1
	ds_bpermute_b32 v195, v239, v194
	ds_bpermute_b32 v199, v239, v198
	ds_bpermute_b32 v203, v239, v202
	ds_bpermute_b32 v207, v239, v206
	ds_bpermute_b32 v211, v239, v210
	ds_bpermute_b32 v215, v239, v214
	ds_bpermute_b32 v219, v239, v218
	ds_bpermute_b32 v223, v239, v222
	s_waitcnt lgkmcnt(7)
	v_add_f32_e32 v194, v194, v195
	s_waitcnt lgkmcnt(6)
	v_add_f32_e32 v198, v198, v199
	s_waitcnt lgkmcnt(5)
	v_add_f32_e32 v202, v202, v203
	s_waitcnt lgkmcnt(4)
	v_add_f32_e32 v206, v206, v207
	s_waitcnt lgkmcnt(3)
	v_add_f32_e32 v210, v210, v211
	s_waitcnt lgkmcnt(2)
	v_add_f32_e32 v214, v214, v215
	s_waitcnt lgkmcnt(1)
	v_add_f32_e32 v218, v218, v219
	s_waitcnt lgkmcnt(0)
	v_add_f32_e32 v222, v222, v223
	v_fma_f32 v194, v194, s48, v241
	v_fma_f32 v198, v198, s48, v241
	v_fma_f32 v202, v202, s48, v241
	v_fma_f32 v206, v206, s48, v241
	v_fma_f32 v210, v210, s48, v241
	v_fma_f32 v214, v214, s48, v241
	v_fma_f32 v218, v218, s48, v241
	v_fma_f32 v222, v222, s48, v241
	v_rsq_f32_e32 v194, v194
	v_rsq_f32_e32 v198, v198
	v_rsq_f32_e32 v202, v202
	v_rsq_f32_e32 v206, v206
	v_rsq_f32_e32 v210, v210
	v_rsq_f32_e32 v214, v214
	v_rsq_f32_e32 v218, v218
	v_rsq_f32_e32 v222, v222
	v_pk_mul_f32 v[172:173], v[172:173], v[194:195] op_sel_hi:[1,0]
	v_pk_mul_f32 v[174:175], v[174:175], v[198:199] op_sel_hi:[1,0]
	v_pk_mul_f32 v[176:177], v[176:177], v[202:203] op_sel_hi:[1,0]
	v_pk_mul_f32 v[178:179], v[178:179], v[206:207] op_sel_hi:[1,0]
	v_pk_mul_f32 v[180:181], v[180:181], v[210:211] op_sel_hi:[1,0]
	v_pk_mul_f32 v[182:183], v[182:183], v[214:215] op_sel_hi:[1,0]
	v_pk_mul_f32 v[184:185], v[184:185], v[218:219] op_sel_hi:[1,0]
	v_pk_mul_f32 v[186:187], v[186:187], v[222:223] op_sel_hi:[1,0]
	v_pk_fma_f32 v[172:173], v[172:173], v[92:93], v[94:95]
	v_pk_fma_f32 v[174:175], v[174:175], v[92:93], v[94:95]
	v_pk_fma_f32 v[176:177], v[176:177], v[92:93], v[94:95]
	v_pk_fma_f32 v[178:179], v[178:179], v[92:93], v[94:95]
	v_pk_fma_f32 v[180:181], v[180:181], v[92:93], v[94:95]
	v_pk_fma_f32 v[182:183], v[182:183], v[92:93], v[94:95]
	v_pk_fma_f32 v[184:185], v[184:185], v[92:93], v[94:95]
	v_pk_fma_f32 v[186:187], v[186:187], v[92:93], v[94:95]
	v_pk_mul_f32 v[196:197], v[172:173], s[80:81]
	v_pk_mul_f32 v[200:201], v[174:175], s[80:81]
	v_pk_mul_f32 v[204:205], v[176:177], s[80:81]
	v_pk_mul_f32 v[208:209], v[178:179], s[80:81]
	v_pk_mul_f32 v[212:213], v[180:181], s[80:81]
	v_pk_mul_f32 v[216:217], v[182:183], s[80:81]
	v_pk_mul_f32 v[220:221], v[184:185], s[80:81]
	v_pk_mul_f32 v[224:225], v[186:187], s[80:81]
	v_exp_f32_e32 v196, v196
	v_exp_f32_e32 v197, v197
	v_exp_f32_e32 v200, v200
	v_exp_f32_e32 v201, v201
	v_exp_f32_e32 v204, v204
	v_exp_f32_e32 v205, v205
	v_exp_f32_e32 v208, v208
	v_exp_f32_e32 v209, v209
	v_exp_f32_e32 v212, v212
	v_exp_f32_e32 v213, v213
	v_exp_f32_e32 v216, v216
	v_exp_f32_e32 v217, v217
	v_exp_f32_e32 v220, v220
	v_exp_f32_e32 v221, v221
	v_exp_f32_e32 v224, v224
	v_exp_f32_e32 v225, v225
	v_pk_add_f32 v[196:197], v[196:197], s[86:87]
	v_pk_add_f32 v[200:201], v[200:201], s[86:87]
	v_pk_add_f32 v[204:205], v[204:205], s[86:87]
	v_pk_add_f32 v[208:209], v[208:209], s[86:87]
	v_pk_add_f32 v[212:213], v[212:213], s[86:87]
	v_pk_add_f32 v[216:217], v[216:217], s[86:87]
	v_pk_add_f32 v[220:221], v[220:221], s[86:87]
; __device__ __forceinline__ unsigned pk2(float lo, float hi) { f32x2v v = {lo, hi}; b16x2v b = __builtin_convertvector(v, b16x2v); return __builtin_bit_cast(unsigned, b); }
; __device__ __forceinline__ float fsigmoid(float x) { return __builtin_amdgcn_rcpf(1.0f + __expf(-x)); }
; __device__ __forceinline__ void gn_swish_store(float v0, float v1, f32x2v gg, f32x2v gb, unsigned* dst) {
;     const float mean = half_wave_sum(v0 + v1) * (1.0f / 64.0f); const float d0 = v0 - mean, d1 = v1 - mean;
;     const float rstd = rsqrtf(half_wave_sum(d0 * d0 + d1 * d1) * (1.0f / 64.0f) + LN_EPS);
;     float y0 = d0 * rstd * gg.x + gb.x, y1 = d1 * rstd * gg.y + gb.y;
;     y0 = y0 * fsigmoid(y0); y1 = y1 * fsigmoid(y1);
;     *dst = pk2(y0, y1);
; }
	v_pk_add_f32 v[224:225], v[224:225], s[86:87]
	v_rcp_f32_e32 v196, v196
	v_rcp_f32_e32 v197, v197
	v_rcp_f32_e32 v200, v200
	v_rcp_f32_e32 v201, v201
	v_rcp_f32_e32 v204, v204
	v_rcp_f32_e32 v205, v205
	v_rcp_f32_e32 v208, v208
	v_rcp_f32_e32 v209, v209
	v_rcp_f32_e32 v212, v212
	v_rcp_f32_e32 v213, v213
	v_rcp_f32_e32 v216, v216
	v_rcp_f32_e32 v217, v217
	v_rcp_f32_e32 v220, v220
	v_rcp_f32_e32 v221, v221
	v_rcp_f32_e32 v224, v224
	v_rcp_f32_e32 v225, v225
	v_pk_mul_f32 v[172:173], v[172:173], v[196:197]
	v_pk_mul_f32 v[174:175], v[174:175], v[200:201]
	v_pk_mul_f32 v[176:177], v[176:177], v[204:205]
	v_pk_mul_f32 v[178:179], v[178:179], v[208:209]
	v_pk_mul_f32 v[180:181], v[180:181], v[212:213]
	v_pk_mul_f32 v[182:183], v[182:183], v[216:217]
	v_pk_mul_f32 v[184:185], v[184:185], v[220:221]
	v_pk_mul_f32 v[186:187], v[186:187], v[224:225]
	v_cvt_pk_bf16_f32 v194, v172, v173
	v_cvt_pk_bf16_f32 v198, v174, v175
	v_cvt_pk_bf16_f32 v202, v176, v177
	v_cvt_pk_bf16_f32 v206, v178, v179
	v_cvt_pk_bf16_f32 v210, v180, v181
	v_cvt_pk_bf16_f32 v214, v182, v183
	v_cvt_pk_bf16_f32 v218, v184, v185
	v_cvt_pk_bf16_f32 v222, v186, v187
	global_store_dword v105, v194, s[70:71] offset:-4096 sc1
	global_store_dword v105, v198, s[70:71] offset:-2048 sc1
	global_store_dword v105, v202, s[70:71] offset:0 sc1
	global_store_dword v105, v206, s[70:71] offset:2048 sc1
	s_add_u32 s70, s70, 0x2000
	s_addc_u32 s71, s71, 0
	global_store_dword v105, v210, s[70:71] offset:-4096 sc1
	global_store_dword v105, v214, s[70:71] offset:-2048 sc1
	global_store_dword v105, v218, s[70:71] offset:0 sc1
	global_store_dword v105, v222, s[70:71] offset:2048 sc1
	v_add_f32_e32 v194, v188, v189
	v_add_f32_e32 v198, v190, v191
	v_add_f32_e32 v202, v78, v79
	v_add_f32_e32 v206, v80, v81
	v_add_f32_e32 v210, v82, v83
	v_add_f32_e32 v214, v84, v85
	v_add_f32_e32 v218, v86, v87
	v_add_f32_e32 v222, v88, v89
	v_add_f32_dpp v194, v194, v194 quad_perm:[1,0,3,2] row_mask:0xf bank_mask:0xf bound_ctrl:1
	v_add_f32_dpp v198, v198, v198 quad_perm:[1,0,3,2] row_mask:0xf bank_mask:0xf bound_ctrl:1
	v_add_f32_dpp v202, v202, v202 quad_perm:[1,0,3,2] row_mask:0xf bank_mask:0xf bound_ctrl:1
	v_add_f32_dpp v206, v206, v206 quad_perm:[1,0,3,2] row_mask:0xf bank_mask:0xf bound_ctrl:1
	v_add_f32_dpp v210, v210, v210 quad_perm:[1,0,3,2] row_mask:0xf bank_mask:0xf bound_ctrl:1
	v_add_f32_dpp v214, v214, v214 quad_perm:[1,0,3,2] row_mask:0xf bank_mask:0xf bound_ctrl:1
	v_add_f32_dpp v218, v218, v218 quad_perm:[1,0,3,2] row_mask:0xf bank_mask:0xf bound_ctrl:1
	v_add_f32_dpp v222, v222, v222 quad_perm:[1,0,3,2] row_mask:0xf bank_mask:0xf bound_ctrl:1
	v_add_f32_dpp v194, v194, v194 quad_perm:[2,3,0,1] row_mask:0xf bank_mask:0xf bound_ctrl:1
	v_add_f32_dpp v198, v198, v198 quad_perm:[2,3,0,1] row_mask:0xf bank_mask:0xf bound_ctrl:1
	v_add_f32_dpp v202, v202, v202 quad_perm:[2,3,0,1] row_mask:0xf bank_mask:0xf bound_ctrl:1
	v_add_f32_dpp v206, v206, v206 quad_perm:[2,3,0,1] row_mask:0xf bank_mask:0xf bound_ctrl:1
	v_add_f32_dpp v210, v210, v210 quad_perm:[2,3,0,1] row_mask:0xf bank_mask:0xf bound_ctrl:1
	v_add_f32_dpp v214, v214, v214 quad_perm:[2,3,0,1] row_mask:0xf bank_mask:0xf bound_ctrl:1
	v_add_f32_dpp v218, v218, v218 quad_perm:[2,3,0,1] row_mask:0xf bank_mask:0xf bound_ctrl:1
	v_add_f32_dpp v222, v222, v222 quad_perm:[2,3,0,1] row_mask:0xf bank_mask:0xf bound_ctrl:1
	v_add_f32_dpp v194, v194, v194 row_half_mirror row_mask:0xf bank_mask:0xf bound_ctrl:1
	v_add_f32_dpp v198, v198, v198 row_half_mirror row_mask:0xf bank_mask:0xf bound_ctrl:1
	v_add_f32_dpp v202, v202, v202 row_half_mirror row_mask:0xf bank_mask:0xf bound_ctrl:1
	v_add_f32_dpp v206, v206, v206 row_half_mirror row_mask:0xf bank_mask:0xf bound_ctrl:1
	v_add_f32_dpp v210, v210, v210 row_half_mirror row_mask:0xf bank_mask:0xf bound_ctrl:1
	v_add_f32_dpp v214, v214, v214 row_half_mirror row_mask:0xf bank_mask:0xf bound_ctrl:1
	v_add_f32_dpp v218, v218, v218 row_half_mirror row_mask:0xf bank_mask:0xf bound_ctrl:1
	v_add_f32_dpp v222, v222, v222 row_half_mirror row_mask:0xf bank_mask:0xf bound_ctrl:1
	v_add_f32_dpp v194, v194, v194 row_mirror row_mask:0xf bank_mask:0xf bound_ctrl:1
	v_add_f32_dpp v198, v198, v198 row_mirror row_mask:0xf bank_mask:0xf bound_ctrl:1
	v_add_f32_dpp v202, v202, v202 row_mirror row_mask:0xf bank_mask:0xf bound_ctrl:1
	v_add_f32_dpp v206, v206, v206 row_mirror row_mask:0xf bank_mask:0xf bound_ctrl:1
	v_add_f32_dpp v210, v210, v210 row_mirror row_mask:0xf bank_mask:0xf bound_ctrl:1
	v_add_f32_dpp v214, v214, v214 row_mirror row_mask:0xf bank_mask:0xf bound_ctrl:1
	v_add_f32_dpp v218, v218, v218 row_mirror row_mask:0xf bank_mask:0xf bound_ctrl:1
	v_add_f32_dpp v222, v222, v222 row_mirror row_mask:0xf bank_mask:0xf bound_ctrl:1
	ds_bpermute_b32 v195, v239, v194
	ds_bpermute_b32 v199, v239, v198
	ds_bpermute_b32 v203, v239, v202
	ds_bpermute_b32 v207, v239, v206
	ds_bpermute_b32 v211, v239, v210
	ds_bpermute_b32 v215, v239, v214
	ds_bpermute_b32 v219, v239, v218
	ds_bpermute_b32 v223, v239, v222
	s_waitcnt lgkmcnt(7)
	v_add_f32_e32 v194, v194, v195
	s_waitcnt lgkmcnt(6)
	v_add_f32_e32 v198, v198, v199
	s_waitcnt lgkmcnt(5)
	v_add_f32_e32 v202, v202, v203
	s_waitcnt lgkmcnt(4)
	v_add_f32_e32 v206, v206, v207
	s_waitcnt lgkmcnt(3)
	v_add_f32_e32 v210, v210, v211
	s_waitcnt lgkmcnt(2)
	v_add_f32_e32 v214, v214, v215
	s_waitcnt lgkmcnt(1)
	v_add_f32_e32 v218, v218, v219
	s_waitcnt lgkmcnt(0)
; template <int CTRL> __device__ __forceinline__ float dpp_mov(float v) { return __builtin_bit_cast(float, __builtin_amdgcn_update_dpp(0, __builtin_bit_cast(int, v), CTRL, 0xf, 0xf, true)); }
; __device__ __forceinline__ float half_wave_sum(float v) {
;     v += dpp_mov<0xB1>(v);
;     v += dpp_mov<0x4E>(v);
;     v += dpp_mov<0x141>(v);
;     v += dpp_mov<0x140>(v);
;     v += __shfl_xor(v, 16);
;     return v;
; }
; __device__ __forceinline__ void gn_swish_store(float v0, float v1, f32x2v gg, f32x2v gb, unsigned* dst) {
;     const float mean = half_wave_sum(v0 + v1) * (1.0f / 64.0f); const float d0 = v0 - mean, d1 = v1 - mean;
;     const float rstd = rsqrtf(half_wave_sum(d0 * d0 + d1 * d1) * (1.0f / 64.0f) + LN_EPS);
	v_add_f32_e32 v222, v222, v223
	v_pk_fma_f32 v[188:189], v[194:195], s[78:79], v[188:189] op_sel_hi:[0,1,1]
	v_pk_fma_f32 v[190:191], v[198:199], s[78:79], v[190:191] op_sel_hi:[0,1,1]
	v_pk_fma_f32 v[78:79], v[202:203], s[78:79], v[78:79] op_sel_hi:[0,1,1]
	v_pk_fma_f32 v[80:81], v[206:207], s[78:79], v[80:81] op_sel_hi:[0,1,1]
	v_pk_fma_f32 v[82:83], v[210:211], s[78:79], v[82:83] op_sel_hi:[0,1,1]
	v_pk_fma_f32 v[84:85], v[214:215], s[78:79], v[84:85] op_sel_hi:[0,1,1]
	v_pk_fma_f32 v[86:87], v[218:219], s[78:79], v[86:87] op_sel_hi:[0,1,1]
	v_pk_fma_f32 v[88:89], v[222:223], s[78:79], v[88:89] op_sel_hi:[0,1,1]
	v_pk_mul_f32 v[196:197], v[188:189], v[188:189]
	v_pk_mul_f32 v[200:201], v[190:191], v[190:191]
	v_pk_mul_f32 v[204:205], v[78:79], v[78:79]
	v_pk_mul_f32 v[208:209], v[80:81], v[80:81]
	v_pk_mul_f32 v[212:213], v[82:83], v[82:83]
	v_pk_mul_f32 v[216:217], v[84:85], v[84:85]
	v_pk_mul_f32 v[220:221], v[86:87], v[86:87]
	v_pk_mul_f32 v[224:225], v[88:89], v[88:89]
	v_add_f32_e32 v194, v196, v197
	v_add_f32_e32 v198, v200, v201
	v_add_f32_e32 v202, v204, v205
	v_add_f32_e32 v206, v208, v209
	v_add_f32_e32 v210, v212, v213
	v_add_f32_e32 v214, v216, v217
	v_add_f32_e32 v218, v220, v221
	v_add_f32_e32 v222, v224, v225
	v_add_f32_dpp v194, v194, v194 quad_perm:[1,0,3,2] row_mask:0xf bank_mask:0xf bound_ctrl:1
	v_add_f32_dpp v198, v198, v198 quad_perm:[1,0,3,2] row_mask:0xf bank_mask:0xf bound_ctrl:1
	v_add_f32_dpp v202, v202, v202 quad_perm:[1,0,3,2] row_mask:0xf bank_mask:0xf bound_ctrl:1
	v_add_f32_dpp v206, v206, v206 quad_perm:[1,0,3,2] row_mask:0xf bank_mask:0xf bound_ctrl:1
	v_add_f32_dpp v210, v210, v210 quad_perm:[1,0,3,2] row_mask:0xf bank_mask:0xf bound_ctrl:1
	v_add_f32_dpp v214, v214, v214 quad_perm:[1,0,3,2] row_mask:0xf bank_mask:0xf bound_ctrl:1
	v_add_f32_dpp v218, v218, v218 quad_perm:[1,0,3,2] row_mask:0xf bank_mask:0xf bound_ctrl:1
	v_add_f32_dpp v222, v222, v222 quad_perm:[1,0,3,2] row_mask:0xf bank_mask:0xf bound_ctrl:1
	v_add_f32_dpp v194, v194, v194 quad_perm:[2,3,0,1] row_mask:0xf bank_mask:0xf bound_ctrl:1
	v_add_f32_dpp v198, v198, v198 quad_perm:[2,3,0,1] row_mask:0xf bank_mask:0xf bound_ctrl:1
	v_add_f32_dpp v202, v202, v202 quad_perm:[2,3,0,1] row_mask:0xf bank_mask:0xf bound_ctrl:1
	v_add_f32_dpp v206, v206, v206 quad_perm:[2,3,0,1] row_mask:0xf bank_mask:0xf bound_ctrl:1
	v_add_f32_dpp v210, v210, v210 quad_perm:[2,3,0,1] row_mask:0xf bank_mask:0xf bound_ctrl:1
	v_add_f32_dpp v214, v214, v214 quad_perm:[2,3,0,1] row_mask:0xf bank_mask:0xf bound_ctrl:1
	v_add_f32_dpp v218, v218, v218 quad_perm:[2,3,0,1] row_mask:0xf bank_mask:0xf bound_ctrl:1
	v_add_f32_dpp v222, v222, v222 quad_perm:[2,3,0,1] row_mask:0xf bank_mask:0xf bound_ctrl:1
	v_add_f32_dpp v194, v194, v194 row_half_mirror row_mask:0xf bank_mask:0xf bound_ctrl:1
	v_add_f32_dpp v198, v198, v198 row_half_mirror row_mask:0xf bank_mask:0xf bound_ctrl:1
	v_add_f32_dpp v202, v202, v202 row_half_mirror row_mask:0xf bank_mask:0xf bound_ctrl:1
	v_add_f32_dpp v206, v206, v206 row_half_mirror row_mask:0xf bank_mask:0xf bound_ctrl:1
	v_add_f32_dpp v210, v210, v210 row_half_mirror row_mask:0xf bank_mask:0xf bound_ctrl:1
	v_add_f32_dpp v214, v214, v214 row_half_mirror row_mask:0xf bank_mask:0xf bound_ctrl:1
	v_add_f32_dpp v218, v218, v218 row_half_mirror row_mask:0xf bank_mask:0xf bound_ctrl:1
	v_add_f32_dpp v222, v222, v222 row_half_mirror row_mask:0xf bank_mask:0xf bound_ctrl:1
	v_add_f32_dpp v194, v194, v194 row_mirror row_mask:0xf bank_mask:0xf bound_ctrl:1
	v_add_f32_dpp v198, v198, v198 row_mirror row_mask:0xf bank_mask:0xf bound_ctrl:1
	v_add_f32_dpp v202, v202, v202 row_mirror row_mask:0xf bank_mask:0xf bound_ctrl:1
	v_add_f32_dpp v206, v206, v206 row_mirror row_mask:0xf bank_mask:0xf bound_ctrl:1
	v_add_f32_dpp v210, v210, v210 row_mirror row_mask:0xf bank_mask:0xf bound_ctrl:1
	v_add_f32_dpp v214, v214, v214 row_mirror row_mask:0xf bank_mask:0xf bound_ctrl:1
	v_add_f32_dpp v218, v218, v218 row_mirror row_mask:0xf bank_mask:0xf bound_ctrl:1
	v_add_f32_dpp v222, v222, v222 row_mirror row_mask:0xf bank_mask:0xf bound_ctrl:1
	ds_bpermute_b32 v195, v239, v194
	ds_bpermute_b32 v199, v239, v198
	ds_bpermute_b32 v203, v239, v202
	ds_bpermute_b32 v207, v239, v206
	ds_bpermute_b32 v211, v239, v210
	ds_bpermute_b32 v215, v239, v214
	ds_bpermute_b32 v219, v239, v218
	ds_bpermute_b32 v223, v239, v222
	s_waitcnt lgkmcnt(7)
	v_add_f32_e32 v194, v194, v195
	s_waitcnt lgkmcnt(6)
	v_add_f32_e32 v198, v198, v199
	s_waitcnt lgkmcnt(5)
; __device__ __forceinline__ unsigned pk2(float lo, float hi) { f32x2v v = {lo, hi}; b16x2v b = __builtin_convertvector(v, b16x2v); return __builtin_bit_cast(unsigned, b); }
; __device__ __forceinline__ float fsigmoid(float x) { return __builtin_amdgcn_rcpf(1.0f + __expf(-x)); }
; __device__ __forceinline__ void gn_swish_store(float v0, float v1, f32x2v gg, f32x2v gb, unsigned* dst) {
;     const float mean = half_wave_sum(v0 + v1) * (1.0f / 64.0f); const float d0 = v0 - mean, d1 = v1 - mean;
;     const float rstd = rsqrtf(half_wave_sum(d0 * d0 + d1 * d1) * (1.0f / 64.0f) + LN_EPS);
;     float y0 = d0 * rstd * gg.x + gb.x, y1 = d1 * rstd * gg.y + gb.y;
;     y0 = y0 * fsigmoid(y0); y1 = y1 * fsigmoid(y1);
;     *dst = pk2(y0, y1);
; }
	v_add_f32_e32 v202, v202, v203
	s_waitcnt lgkmcnt(4)
	v_add_f32_e32 v206, v206, v207
	s_waitcnt lgkmcnt(3)
	v_add_f32_e32 v210, v210, v211
	s_waitcnt lgkmcnt(2)
	v_add_f32_e32 v214, v214, v215
	s_waitcnt lgkmcnt(1)
	v_add_f32_e32 v218, v218, v219
	s_waitcnt lgkmcnt(0)
	v_add_f32_e32 v222, v222, v223
	v_fma_f32 v194, v194, s48, v241
	v_fma_f32 v198, v198, s48, v241
	v_fma_f32 v202, v202, s48, v241
	v_fma_f32 v206, v206, s48, v241
	v_fma_f32 v210, v210, s48, v241
	v_fma_f32 v214, v214, s48, v241
	v_fma_f32 v218, v218, s48, v241
	v_fma_f32 v222, v222, s48, v241
	v_rsq_f32_e32 v194, v194
	v_rsq_f32_e32 v198, v198
	v_rsq_f32_e32 v202, v202
	v_rsq_f32_e32 v206, v206
	v_rsq_f32_e32 v210, v210
	v_rsq_f32_e32 v214, v214
	v_rsq_f32_e32 v218, v218
	v_rsq_f32_e32 v222, v222
	v_pk_mul_f32 v[188:189], v[188:189], v[194:195] op_sel_hi:[1,0]
	v_pk_mul_f32 v[190:191], v[190:191], v[198:199] op_sel_hi:[1,0]
	v_pk_mul_f32 v[78:79], v[78:79], v[202:203] op_sel_hi:[1,0]
	v_pk_mul_f32 v[80:81], v[80:81], v[206:207] op_sel_hi:[1,0]
	v_pk_mul_f32 v[82:83], v[82:83], v[210:211] op_sel_hi:[1,0]
	v_pk_mul_f32 v[84:85], v[84:85], v[214:215] op_sel_hi:[1,0]
	v_pk_mul_f32 v[86:87], v[86:87], v[218:219] op_sel_hi:[1,0]
	v_pk_mul_f32 v[88:89], v[88:89], v[222:223] op_sel_hi:[1,0]
	v_pk_fma_f32 v[188:189], v[188:189], v[92:93], v[94:95]
	v_pk_fma_f32 v[190:191], v[190:191], v[92:93], v[94:95]
	v_pk_fma_f32 v[78:79], v[78:79], v[92:93], v[94:95]
	v_pk_fma_f32 v[80:81], v[80:81], v[92:93], v[94:95]
	v_pk_fma_f32 v[82:83], v[82:83], v[92:93], v[94:95]
	v_pk_fma_f32 v[84:85], v[84:85], v[92:93], v[94:95]
	v_pk_fma_f32 v[86:87], v[86:87], v[92:93], v[94:95]
	v_pk_fma_f32 v[88:89], v[88:89], v[92:93], v[94:95]
	v_pk_mul_f32 v[196:197], v[188:189], s[80:81]
	v_pk_mul_f32 v[200:201], v[190:191], s[80:81]
	v_pk_mul_f32 v[204:205], v[78:79], s[80:81]
	v_pk_mul_f32 v[208:209], v[80:81], s[80:81]
	v_pk_mul_f32 v[212:213], v[82:83], s[80:81]
	v_pk_mul_f32 v[216:217], v[84:85], s[80:81]
	v_pk_mul_f32 v[220:221], v[86:87], s[80:81]
	v_pk_mul_f32 v[224:225], v[88:89], s[80:81]
	v_exp_f32_e32 v196, v196
	v_exp_f32_e32 v197, v197
	v_exp_f32_e32 v200, v200
	v_exp_f32_e32 v201, v201
	v_exp_f32_e32 v204, v204
	v_exp_f32_e32 v205, v205
	v_exp_f32_e32 v208, v208
	v_exp_f32_e32 v209, v209
	v_exp_f32_e32 v212, v212
	v_exp_f32_e32 v213, v213
	v_exp_f32_e32 v216, v216
	v_exp_f32_e32 v217, v217
	v_exp_f32_e32 v220, v220
	v_exp_f32_e32 v221, v221
	v_exp_f32_e32 v224, v224
	v_exp_f32_e32 v225, v225
	v_pk_add_f32 v[196:197], v[196:197], s[86:87]
	v_pk_add_f32 v[200:201], v[200:201], s[86:87]
	v_pk_add_f32 v[204:205], v[204:205], s[86:87]
	v_pk_add_f32 v[208:209], v[208:209], s[86:87]
	v_pk_add_f32 v[212:213], v[212:213], s[86:87]
	v_pk_add_f32 v[216:217], v[216:217], s[86:87]
	v_pk_add_f32 v[220:221], v[220:221], s[86:87]
	v_pk_add_f32 v[224:225], v[224:225], s[86:87]
	v_rcp_f32_e32 v196, v196
	v_rcp_f32_e32 v197, v197
	v_rcp_f32_e32 v200, v200
	v_rcp_f32_e32 v201, v201
	v_rcp_f32_e32 v204, v204
	v_rcp_f32_e32 v205, v205
	v_rcp_f32_e32 v208, v208
	v_rcp_f32_e32 v209, v209
	v_rcp_f32_e32 v212, v212
	v_rcp_f32_e32 v213, v213
	v_rcp_f32_e32 v216, v216
	v_rcp_f32_e32 v217, v217
	v_rcp_f32_e32 v220, v220
	v_rcp_f32_e32 v221, v221
	v_rcp_f32_e32 v224, v224
	v_rcp_f32_e32 v225, v225
	v_pk_mul_f32 v[188:189], v[188:189], v[196:197]
	v_pk_mul_f32 v[190:191], v[190:191], v[200:201]
	v_pk_mul_f32 v[78:79], v[78:79], v[204:205]
	v_pk_mul_f32 v[80:81], v[80:81], v[208:209]
	v_pk_mul_f32 v[82:83], v[82:83], v[212:213]
	v_pk_mul_f32 v[84:85], v[84:85], v[216:217]
	v_pk_mul_f32 v[86:87], v[86:87], v[220:221]
	v_pk_mul_f32 v[88:89], v[88:89], v[224:225]
	v_cvt_pk_bf16_f32 v194, v188, v189
	v_cvt_pk_bf16_f32 v198, v190, v191
	v_cvt_pk_bf16_f32 v202, v78, v79
	v_cvt_pk_bf16_f32 v206, v80, v81
	v_cvt_pk_bf16_f32 v210, v82, v83
	v_cvt_pk_bf16_f32 v214, v84, v85
	v_cvt_pk_bf16_f32 v218, v86, v87
	v_cvt_pk_bf16_f32 v222, v88, v89
	s_add_u32 s70, s70, 0x2000
	s_addc_u32 s71, s71, 0
	global_store_dword v105, v194, s[70:71] offset:-4096 sc1
	global_store_dword v105, v198, s[70:71] offset:-2048 sc1
	global_store_dword v105, v202, s[70:71] offset:0 sc1
	global_store_dword v105, v206, s[70:71] offset:2048 sc1
	s_add_u32 s70, s70, 0x2000
	s_addc_u32 s71, s71, 0
	global_store_dword v105, v210, s[70:71] offset:-4096 sc1
	global_store_dword v105, v214, s[70:71] offset:-2048 sc1
	global_store_dword v105, v218, s[70:71] offset:0 sc1
	global_store_dword v105, v222, s[70:71] offset:2048 sc1
	s_branch .Lmx_done
